# combination: first K-loop trip peeled (no accumulator zeroing) + FFN2 walks K downward + hot loop heads 64-byte aligned
# speedup vs baseline: 1.0021x; 1.0021x over previous
; DI int TID() { int t = (int)__builtin_amdgcn_workitem_id_x(); asm volatile("" : "+v"(t)); return t; }
; #define BLOAD(A_, B_, kt) do { _Pragma("unroll") for (int i = 0; i < 4; ++i) { \
;     A_[i] = *(const u32x4*)((const char*)Ap + (aoff + (unsigned)(32 * i * lda + (kt) * 64) * 2u)); B_[i] = *(const u32x4*)((const char*)Wt + (woff + (unsigned)(32 * i * K + (kt) * 64) * 2u)); } } while (0)
; #define BLOAD(A_, B_, kt) do { _Pragma("unroll") for (int i = 0; i < 4; ++i) { \
;     A_[i] = *(const u32x4*)((const char*)Ap + (aoff + (unsigned)(32 * i * lda + (kt) * 64) * 2u)); B_[i] = *(const u32x4*)((const char*)Wt + (woff + (unsigned)(32 * i * K + (kt) * 64) * 2u)); } } while (0)
; #define BSTORE(A_, B_, buf) do { _Pragma("unroll") for (int i = 0; i < 4; ++i) { \
;     *(u32x4*)&As[(buf) * GBUF + (srow + 32 * i) * LDT + sc8] = A_[i]; \
;     *(u32x4*)&Bs[(buf) * GBUF + (srow + 32 * i) * LDT + sc8] = B_[i]; } } while (0)
; template <int NK>
; DI void gemm_run(PF& pf, const u16* __restrict__ Ap, int lda, const u16* __restrict__ Wt, f32x16 (&acc)[2][2], char* smem) {
;     ...
;   __builtin_amdgcn_s_setprio(0);
;   __syncthreads();
;   BSTORE(pf.a0, pf.b0, 0);
;   BLOAD(pf.a0, pf.b0, 2);
;   __syncthreads();
; #pragma unroll
;   for (int kt = 0; kt < nk; kt += 2) {
;     BCOMP(0);
;     BSTORE(pf.a1, pf.b1, 1);
;     if (kt + 3 < nk) BLOAD(pf.a1, pf.b1, kt + 3);
;     __syncthreads();
; DI void tile_ffn2(const Params& p, int l, const Chunk& ck, int tile, int next, PF& pf, char* smem) {
;   float* Cs = (float*)smem;
;   const int tid = TID(); const int mi = tile & (MTN - 1), ni = tile >> MTS; const int m0 = mi * 128, n0 = ni * 128;
;   f32x16 acc[2][2]; zero_acc(acc);
;   { const u16* Ap; const u16* Wt; ffn2_ptrs(p, l, tile, Ap, Wt); gemm_run<64>(pf, Ap, 4096, Wt, acc, smem); }
.LBB1_206:
	s_add_i32 s25, s26, s78
	s_cmpk_gt_i32 s25, 0x1ff
	s_cselect_b64 s[28:29], -1, 0
	s_cmpk_lt_i32 s25, 0x200
	s_cselect_b32 s0, s25, -1
	s_and_b32 s16, s41, 0x3f80000
	s_and_b32 s36, s26, 0xffffff80
	s_add_i32 s26, s26, s36
	s_lshl_b32 s36, s36, 1
	s_lshl_b32 s16, s16, 1
	s_add_u32 vcc_lo, s17, s16
	v_mov_b32_e32 v0, v172
	s_addc_u32 vcc_hi, s27, 0
	s_ashr_i32 s37, s36, 31
	s_lshl_b64 s[30:31], s[36:37], 6
	s_add_u32 s30, s34, s30
	s_addc_u32 s31, s40, s31
	s_setprio 0
	s_waitcnt lgkmcnt(0)
	s_lshr_b32 s16, s16, 7
	s_add_u32 s42, s17, s16
	s_addc_u32 s43, s27, 0
	s_add_u32 s42, s42, 0x7f00000
	s_addc_u32 s43, s43, 0
	s_add_u32 s30, s30, 0x7f0000
	s_addc_u32 s31, s31, 0
	v_and_b32_e32 v174, 63, v172
	v_lshrrev_b32_e32 v175, 6, v172
	v_bfe_u32 v176, v174, 4, 2
	v_lshrrev_b32_e32 v177, 1, v176
	v_xor_b32_e32 v176, v176, v177
	v_and_b32_e32 v176, 1, v176
	v_lshl_or_b32 v176, v176, 1, v177
	v_xor_b32_e32 v176, v176, v174
	v_and_b32_e32 v176, 3, v176
	v_lshlrev_b32_e32 v176, 4, v176
	v_lshrrev_b32_e32 v177, 2, v174
	v_lshl_add_u32 v137, v175, 5, v177
	v_lshl_add_u32 v137, v137, 6, v176
	v_mov_b32_e32 v150, v137
	v_lshl_add_u32 v151, v175, 6, v177
	v_lshl_add_u32 v151, v151, 6, v176
	v_mov_b32_e32 v152, v151
	v_mov_b32_e32 v153, v151
	v_mov_b32_e32 v154, v151
	v_readfirstlane_b32 s16, v175
	s_lshl_b32 s0, s16, 12
	s_lshl_b32 s16, s16, 11
	s_add_u32 s0, s0, 0x2000
	v_bfe_u32 v176, v174, 2, 2
	v_lshrrev_b32_e32 v177, 1, v176
	v_xor_b32_e32 v176, v176, v177
	v_and_b32_e32 v176, 1, v176
	v_lshl_or_b32 v176, v176, 1, v177
	v_lshrrev_b32_e32 v177, 4, v174
	v_xor_b32_e32 v176, v176, v177
	v_lshlrev_b32_e32 v176, 4, v176
	v_and_b32_e32 v174, 15, v174
	v_lshl_add_u32 v174, v174, 6, v176
	v_lshrrev_b32_e32 v176, 1, v175
	v_and_b32_e32 v177, 1, v175
	v_lshl_add_u32 v126, v176, 12, v174
	v_lshl_add_u32 v128, v177, 12, v174
	v_add_u32_e32 v128, 0x2000, v128
	s_barrier
	s_add_u32 m0, s16, 0x0
	s_nop 0
	global_load_lds_dwordx4 v137, s[42:43]
	global_load_lds_dwordx4 v150, s[42:43] offset:1024
	s_add_u32 m0, s0, 0x0
	s_nop 0
	global_load_lds_dwordx4 v151, s[30:31]
	global_load_lds_dwordx4 v152, s[30:31] offset:1024
	global_load_lds_dwordx4 v153, s[30:31] offset:2048
	global_load_lds_dwordx4 v154, s[30:31] offset:3072
	s_add_u32 m0, s16, 0x6000
	s_sub_u32 s42, s42, 0x100000
	s_subb_u32 s43, s43, 0
	global_load_lds_dwordx4 v137, s[42:43]
	global_load_lds_dwordx4 v150, s[42:43] offset:1024
	s_add_u32 m0, s0, 0x6000
	s_sub_u32 s30, s30, 0x10000
	s_subb_u32 s31, s31, 0
	global_load_lds_dwordx4 v151, s[30:31]
	global_load_lds_dwordx4 v152, s[30:31] offset:1024
	global_load_lds_dwordx4 v153, s[30:31] offset:2048
	global_load_lds_dwordx4 v154, s[30:31] offset:3072
	s_waitcnt vmcnt(6)
	s_barrier
	ds_read_b128 v[224:227], v126 offset:0
	ds_read_b128 v[240:243], v128 offset:0
	ds_read_b128 v[244:247], v128 offset:1024
	ds_read_b128 v[248:251], v128 offset:2048
	ds_read_b128 v[156:159], v128 offset:3072
	s_add_u32 m0, s16, 0xc000
	s_sub_u32 s42, s42, 0x100000
	s_subb_u32 s43, s43, 0
	global_load_lds_dwordx4 v137, s[42:43]
	global_load_lds_dwordx4 v150, s[42:43] offset:1024
	s_add_u32 m0, s0, 0xc000
	s_sub_u32 s30, s30, 0x10000
	s_subb_u32 s31, s31, 0
	global_load_lds_dwordx4 v151, s[30:31]
	global_load_lds_dwordx4 v152, s[30:31] offset:1024
	global_load_lds_dwordx4 v153, s[30:31] offset:2048
	global_load_lds_dwordx4 v154, s[30:31] offset:3072
	ds_read_b128 v[228:231], v126 offset:1024
	ds_read_b128 v[232:235], v126 offset:2048
	ds_read_b128 v[236:239], v126 offset:3072
	ds_read_b128 v[160:163], v128 offset:8192
	ds_read_b128 v[164:167], v128 offset:9216
	ds_read_b128 v[168:171], v128 offset:10240
	ds_read_b128 v[122:125], v128 offset:11264
	s_waitcnt lgkmcnt(10)
	v_mfma_f32_16x16x32_bf16 v[2:5], v[240:243], v[224:227], 0
	s_waitcnt lgkmcnt(9)
	v_mfma_f32_16x16x32_bf16 v[6:9], v[244:247], v[224:227], 0
	s_waitcnt lgkmcnt(8)
	v_mfma_f32_16x16x32_bf16 v[10:13], v[248:251], v[224:227], 0
	s_waitcnt lgkmcnt(7)
	v_mfma_f32_16x16x32_bf16 v[14:17], v[156:159], v[224:227], 0
	s_waitcnt lgkmcnt(6)
	v_mfma_f32_16x16x32_bf16 v[18:21], v[240:243], v[228:231], 0
	v_mfma_f32_16x16x32_bf16 v[22:25], v[244:247], v[228:231], 0
	v_mfma_f32_16x16x32_bf16 v[26:29], v[248:251], v[228:231], 0
	v_mfma_f32_16x16x32_bf16 v[30:33], v[156:159], v[228:231], 0
	s_waitcnt lgkmcnt(5)
	v_mfma_f32_16x16x32_bf16 v[34:37], v[240:243], v[232:235], 0
	v_mfma_f32_16x16x32_bf16 v[38:41], v[244:247], v[232:235], 0
	v_mfma_f32_16x16x32_bf16 v[42:45], v[248:251], v[232:235], 0
	v_mfma_f32_16x16x32_bf16 v[46:49], v[156:159], v[232:235], 0
	s_waitcnt lgkmcnt(4)
	v_mfma_f32_16x16x32_bf16 v[50:53], v[240:243], v[236:239], 0
	v_mfma_f32_16x16x32_bf16 v[54:57], v[244:247], v[236:239], 0
	v_mfma_f32_16x16x32_bf16 v[58:61], v[248:251], v[236:239], 0
	v_mfma_f32_16x16x32_bf16 v[62:65], v[156:159], v[236:239], 0
	s_waitcnt lgkmcnt(3)
	v_mfma_f32_16x16x32_bf16 v[74:77], v[160:163], v[224:227], 0
	s_waitcnt lgkmcnt(2)
	v_mfma_f32_16x16x32_bf16 v[78:81], v[164:167], v[224:227], 0
	s_waitcnt lgkmcnt(1)
	v_mfma_f32_16x16x32_bf16 v[82:85], v[168:171], v[224:227], 0
	s_waitcnt lgkmcnt(0)
	v_mfma_f32_16x16x32_bf16 v[86:89], v[122:125], v[224:227], 0
	v_mfma_f32_16x16x32_bf16 v[90:93], v[160:163], v[228:231], 0
	v_mfma_f32_16x16x32_bf16 v[94:97], v[164:167], v[228:231], 0
	v_mfma_f32_16x16x32_bf16 v[98:101], v[168:171], v[228:231], 0
	v_mfma_f32_16x16x32_bf16 v[102:105], v[122:125], v[228:231], 0
	v_mfma_f32_16x16x32_bf16 v[106:109], v[160:163], v[232:235], 0
	v_mfma_f32_16x16x32_bf16 v[110:113], v[164:167], v[232:235], 0
	v_mfma_f32_16x16x32_bf16 v[114:117], v[168:171], v[232:235], 0
	v_mfma_f32_16x16x32_bf16 v[118:121], v[122:125], v[232:235], 0
	v_mfma_f32_16x16x32_bf16 v[208:211], v[160:163], v[236:239], 0
	v_mfma_f32_16x16x32_bf16 v[212:215], v[164:167], v[236:239], 0
	v_mfma_f32_16x16x32_bf16 v[216:219], v[168:171], v[236:239], 0
	v_mfma_f32_16x16x32_bf16 v[220:223], v[122:125], v[236:239], 0
	s_waitcnt vmcnt(6)
	s_barrier
; #define BLOAD(A_, B_, kt) do { _Pragma("unroll") for (int i = 0; i < 4; ++i) { \
;     A_[i] = *(const u32x4*)((const char*)Ap + (aoff + (unsigned)(32 * i * lda + (kt) * 64) * 2u)); B_[i] = *(const u32x4*)((const char*)Wt + (woff + (unsigned)(32 * i * K + (kt) * 64) * 2u)); } } while (0)
; #define BLOAD(A_, B_, kt) do { _Pragma("unroll") for (int i = 0; i < 4; ++i) { \
;     A_[i] = *(const u32x4*)((const char*)Ap + (aoff + (unsigned)(32 * i * lda + (kt) * 64) * 2u)); B_[i] = *(const u32x4*)((const char*)Wt + (woff + (unsigned)(32 * i * K + (kt) * 64) * 2u)); } } while (0)
; #define BSTORE(A_, B_, buf) do { _Pragma("unroll") for (int i = 0; i < 4; ++i) { \
;     *(u32x4*)&As[(buf) * GBUF + (srow + 32 * i) * LDT + sc8] = A_[i]; \
;     *(u32x4*)&Bs[(buf) * GBUF + (srow + 32 * i) * LDT + sc8] = B_[i]; } } while (0)
; template <int NK>
; DI void gemm_run(PF& pf, const u16* __restrict__ Ap, int lda, const u16* __restrict__ Wt, f32x16 (&acc)[2][2], char* smem) {
;     ...
; #pragma unroll
;   for (int kt = 0; kt < nk; kt += 2) {
;     BCOMP(0);
;     BSTORE(pf.a1, pf.b1, 1);
;     if (kt + 3 < nk) BLOAD(pf.a1, pf.b1, kt + 3);
;     __syncthreads();
;     BCOMP(1);
;     if (kt + 2 < nk) { BSTORE(pf.a0, pf.b0, 0); if (kt + 4 < nk) BLOAD(pf.a0, pf.b0, kt + 4); }
;     __syncthreads();
;   }
	ds_read_b128 v[224:227], v126 offset:24576
	ds_read_b128 v[240:243], v128 offset:24576
	ds_read_b128 v[244:247], v128 offset:25600
	ds_read_b128 v[248:251], v128 offset:26624
	ds_read_b128 v[156:159], v128 offset:27648
	s_add_u32 m0, s16, 0x0
	s_sub_u32 s42, s42, 0x100000
	s_subb_u32 s43, s43, 0
	global_load_lds_dwordx4 v137, s[42:43]
	global_load_lds_dwordx4 v150, s[42:43] offset:1024
	s_add_u32 m0, s0, 0x0
	s_sub_u32 s30, s30, 0x10000
	s_subb_u32 s31, s31, 0
	global_load_lds_dwordx4 v151, s[30:31]
	global_load_lds_dwordx4 v152, s[30:31] offset:1024
	global_load_lds_dwordx4 v153, s[30:31] offset:2048
	global_load_lds_dwordx4 v154, s[30:31] offset:3072
	ds_read_b128 v[228:231], v126 offset:25600
	ds_read_b128 v[232:235], v126 offset:26624
	ds_read_b128 v[236:239], v126 offset:27648
	ds_read_b128 v[160:163], v128 offset:32768
	ds_read_b128 v[164:167], v128 offset:33792
	ds_read_b128 v[168:171], v128 offset:34816
	ds_read_b128 v[122:125], v128 offset:35840
	s_waitcnt lgkmcnt(10)
	v_mfma_f32_16x16x32_bf16 v[2:5], v[240:243], v[224:227], v[2:5]
	s_waitcnt lgkmcnt(9)
	v_mfma_f32_16x16x32_bf16 v[6:9], v[244:247], v[224:227], v[6:9]
	s_waitcnt lgkmcnt(8)
	v_mfma_f32_16x16x32_bf16 v[10:13], v[248:251], v[224:227], v[10:13]
	s_waitcnt lgkmcnt(7)
	v_mfma_f32_16x16x32_bf16 v[14:17], v[156:159], v[224:227], v[14:17]
	s_waitcnt lgkmcnt(6)
	v_mfma_f32_16x16x32_bf16 v[18:21], v[240:243], v[228:231], v[18:21]
	v_mfma_f32_16x16x32_bf16 v[22:25], v[244:247], v[228:231], v[22:25]
	v_mfma_f32_16x16x32_bf16 v[26:29], v[248:251], v[228:231], v[26:29]
	v_mfma_f32_16x16x32_bf16 v[30:33], v[156:159], v[228:231], v[30:33]
	s_waitcnt lgkmcnt(5)
	v_mfma_f32_16x16x32_bf16 v[34:37], v[240:243], v[232:235], v[34:37]
	v_mfma_f32_16x16x32_bf16 v[38:41], v[244:247], v[232:235], v[38:41]
	v_mfma_f32_16x16x32_bf16 v[42:45], v[248:251], v[232:235], v[42:45]
	v_mfma_f32_16x16x32_bf16 v[46:49], v[156:159], v[232:235], v[46:49]
	s_waitcnt lgkmcnt(4)
	v_mfma_f32_16x16x32_bf16 v[50:53], v[240:243], v[236:239], v[50:53]
	v_mfma_f32_16x16x32_bf16 v[54:57], v[244:247], v[236:239], v[54:57]
	v_mfma_f32_16x16x32_bf16 v[58:61], v[248:251], v[236:239], v[58:61]
	v_mfma_f32_16x16x32_bf16 v[62:65], v[156:159], v[236:239], v[62:65]
	s_waitcnt lgkmcnt(3)
	v_mfma_f32_16x16x32_bf16 v[74:77], v[160:163], v[224:227], v[74:77]
	s_waitcnt lgkmcnt(2)
	v_mfma_f32_16x16x32_bf16 v[78:81], v[164:167], v[224:227], v[78:81]
	s_waitcnt lgkmcnt(1)
	v_mfma_f32_16x16x32_bf16 v[82:85], v[168:171], v[224:227], v[82:85]
	s_waitcnt lgkmcnt(0)
	v_mfma_f32_16x16x32_bf16 v[86:89], v[122:125], v[224:227], v[86:89]
	v_mfma_f32_16x16x32_bf16 v[90:93], v[160:163], v[228:231], v[90:93]
	v_mfma_f32_16x16x32_bf16 v[94:97], v[164:167], v[228:231], v[94:97]
	v_mfma_f32_16x16x32_bf16 v[98:101], v[168:171], v[228:231], v[98:101]
	v_mfma_f32_16x16x32_bf16 v[102:105], v[122:125], v[228:231], v[102:105]
	v_mfma_f32_16x16x32_bf16 v[106:109], v[160:163], v[232:235], v[106:109]
	v_mfma_f32_16x16x32_bf16 v[110:113], v[164:167], v[232:235], v[110:113]
	v_mfma_f32_16x16x32_bf16 v[114:117], v[168:171], v[232:235], v[114:117]
	v_mfma_f32_16x16x32_bf16 v[118:121], v[122:125], v[232:235], v[118:121]
	v_mfma_f32_16x16x32_bf16 v[208:211], v[160:163], v[236:239], v[208:211]
	v_mfma_f32_16x16x32_bf16 v[212:215], v[164:167], v[236:239], v[212:215]
	v_mfma_f32_16x16x32_bf16 v[216:219], v[168:171], v[236:239], v[216:219]
	v_mfma_f32_16x16x32_bf16 v[220:223], v[122:125], v[236:239], v[220:223]
	s_waitcnt vmcnt(6)
	s_barrier
	ds_read_b128 v[224:227], v126 offset:49152
	ds_read_b128 v[240:243], v128 offset:49152
	ds_read_b128 v[244:247], v128 offset:50176
	ds_read_b128 v[248:251], v128 offset:51200
	ds_read_b128 v[156:159], v128 offset:52224
	s_add_u32 m0, s16, 0x6000
	s_sub_u32 s42, s42, 0x100000
	s_subb_u32 s43, s43, 0
	global_load_lds_dwordx4 v137, s[42:43]
	global_load_lds_dwordx4 v150, s[42:43] offset:1024
	s_add_u32 m0, s0, 0x6000
	s_sub_u32 s30, s30, 0x10000
	s_subb_u32 s31, s31, 0
	global_load_lds_dwordx4 v151, s[30:31]
	global_load_lds_dwordx4 v152, s[30:31] offset:1024
	global_load_lds_dwordx4 v153, s[30:31] offset:2048
	global_load_lds_dwordx4 v154, s[30:31] offset:3072
	ds_read_b128 v[228:231], v126 offset:50176
	ds_read_b128 v[232:235], v126 offset:51200
	ds_read_b128 v[236:239], v126 offset:52224
	ds_read_b128 v[160:163], v128 offset:57344
	ds_read_b128 v[164:167], v128 offset:58368
	ds_read_b128 v[168:171], v128 offset:59392
	ds_read_b128 v[122:125], v128 offset:60416
	s_waitcnt lgkmcnt(10)
	v_mfma_f32_16x16x32_bf16 v[2:5], v[240:243], v[224:227], v[2:5]
	s_waitcnt lgkmcnt(9)
	v_mfma_f32_16x16x32_bf16 v[6:9], v[244:247], v[224:227], v[6:9]
	s_waitcnt lgkmcnt(8)
	v_mfma_f32_16x16x32_bf16 v[10:13], v[248:251], v[224:227], v[10:13]
	s_waitcnt lgkmcnt(7)
	v_mfma_f32_16x16x32_bf16 v[14:17], v[156:159], v[224:227], v[14:17]
	s_waitcnt lgkmcnt(6)
	v_mfma_f32_16x16x32_bf16 v[18:21], v[240:243], v[228:231], v[18:21]
	v_mfma_f32_16x16x32_bf16 v[22:25], v[244:247], v[228:231], v[22:25]
	v_mfma_f32_16x16x32_bf16 v[26:29], v[248:251], v[228:231], v[26:29]
	v_mfma_f32_16x16x32_bf16 v[30:33], v[156:159], v[228:231], v[30:33]
	s_waitcnt lgkmcnt(5)
	v_mfma_f32_16x16x32_bf16 v[34:37], v[240:243], v[232:235], v[34:37]
	v_mfma_f32_16x16x32_bf16 v[38:41], v[244:247], v[232:235], v[38:41]
	v_mfma_f32_16x16x32_bf16 v[42:45], v[248:251], v[232:235], v[42:45]
	v_mfma_f32_16x16x32_bf16 v[46:49], v[156:159], v[232:235], v[46:49]
	s_waitcnt lgkmcnt(4)
	v_mfma_f32_16x16x32_bf16 v[50:53], v[240:243], v[236:239], v[50:53]
	v_mfma_f32_16x16x32_bf16 v[54:57], v[244:247], v[236:239], v[54:57]
	v_mfma_f32_16x16x32_bf16 v[58:61], v[248:251], v[236:239], v[58:61]
	v_mfma_f32_16x16x32_bf16 v[62:65], v[156:159], v[236:239], v[62:65]
	s_waitcnt lgkmcnt(3)
	v_mfma_f32_16x16x32_bf16 v[74:77], v[160:163], v[224:227], v[74:77]
	s_waitcnt lgkmcnt(2)
	v_mfma_f32_16x16x32_bf16 v[78:81], v[164:167], v[224:227], v[78:81]
	s_waitcnt lgkmcnt(1)
	v_mfma_f32_16x16x32_bf16 v[82:85], v[168:171], v[224:227], v[82:85]
	s_waitcnt lgkmcnt(0)
	v_mfma_f32_16x16x32_bf16 v[86:89], v[122:125], v[224:227], v[86:89]
	v_mfma_f32_16x16x32_bf16 v[90:93], v[160:163], v[228:231], v[90:93]
	v_mfma_f32_16x16x32_bf16 v[94:97], v[164:167], v[228:231], v[94:97]
	v_mfma_f32_16x16x32_bf16 v[98:101], v[168:171], v[228:231], v[98:101]
	v_mfma_f32_16x16x32_bf16 v[102:105], v[122:125], v[228:231], v[102:105]
	v_mfma_f32_16x16x32_bf16 v[106:109], v[160:163], v[232:235], v[106:109]
	v_mfma_f32_16x16x32_bf16 v[110:113], v[164:167], v[232:235], v[110:113]
	v_mfma_f32_16x16x32_bf16 v[114:117], v[168:171], v[232:235], v[114:117]
	v_mfma_f32_16x16x32_bf16 v[118:121], v[122:125], v[232:235], v[118:121]
	v_mfma_f32_16x16x32_bf16 v[208:211], v[160:163], v[236:239], v[208:211]
	v_mfma_f32_16x16x32_bf16 v[212:215], v[164:167], v[236:239], v[212:215]
	v_mfma_f32_16x16x32_bf16 v[216:219], v[168:171], v[236:239], v[216:219]
	v_mfma_f32_16x16x32_bf16 v[220:223], v[122:125], v[236:239], v[220:223]
	s_mov_b32 s46, 41
	.p2align 6

; DI int TID() { int t = (int)__builtin_amdgcn_workitem_id_x(); asm volatile("" : "+v"(t)); return t; }
; #define BLOAD(A_, B_, kt) do { _Pragma("unroll") for (int i = 0; i < 4; ++i) { \
;     A_[i] = *(const u32x4*)((const char*)Ap + (aoff + (unsigned)(32 * i * lda + (kt) * 64) * 2u)); B_[i] = *(const u32x4*)((const char*)Wt + (woff + (unsigned)(32 * i * K + (kt) * 64) * 2u)); } } while (0)
; DI RowSS rowss_load(const float* ps, int m0) { const int tid = TID(); const float* q = ps + (size_t)(m0 + (tid >> 1)) * 16 + (tid & 1) * 8; RowSS r; r.a = *(const f32x4*)q; r.b = *(const f32x4*)(q + 4); return r; }
; #define BLOAD(A_, B_, kt) do { _Pragma("unroll") for (int i = 0; i < 4; ++i) { \
;     A_[i] = *(const u32x4*)((const char*)Ap + (aoff + (unsigned)(32 * i * lda + (kt) * 64) * 2u)); B_[i] = *(const u32x4*)((const char*)Wt + (woff + (unsigned)(32 * i * K + (kt) * 64) * 2u)); } } while (0)
; #define BSTORE(A_, B_, buf) do { _Pragma("unroll") for (int i = 0; i < 4; ++i) { \
;     *(u32x4*)&As[(buf) * GBUF + (srow + 32 * i) * LDT + sc8] = A_[i]; \
;     *(u32x4*)&Bs[(buf) * GBUF + (srow + 32 * i) * LDT + sc8] = B_[i]; } } while (0)
; template <int NK>
; DI void gemm_run(PF& pf, const u16* __restrict__ Ap, int lda, const u16* __restrict__ Wt, f32x16 (&acc)[2][2], char* smem) {
;     ...
;   __builtin_amdgcn_s_setprio(0);
;   __syncthreads();
;   BSTORE(pf.a0, pf.b0, 0);
;   BLOAD(pf.a0, pf.b0, 2);
;   __syncthreads();
; #pragma unroll
;   for (int kt = 0; kt < nk; kt += 2) {
;     BCOMP(0);
;     BSTORE(pf.a1, pf.b1, 1);
;     if (kt + 3 < nk) BLOAD(pf.a1, pf.b1, kt + 3);
;     __syncthreads();
; DI void tile_ffn1(const Params& p, int l, const Chunk& ck, int tile, int next, PF& pf, char* smem) {
;   float* Cs = (float*)smem; float* rinv_s = (float*)(smem + SMEM_CS);
;   const int tid = TID(); const int mi = tile & (MTN - 1), ni = tile >> MTS; const int m0 = mi * 128, n0 = ni * 128;
;   f32x16 acc[2][2]; zero_acc(acc);
;   const RowSS rss = rowss_load((const float*)(p.ws + OFF_PSMID), m0);
;   { const u16* Ap; const u16* Wt; ffn1_ptrs(p, l, tile, Ap, Wt); gemm_run<16>(pf, Ap, 1024, Wt, acc, smem); }
;   if (next >= 0) { const u16* An; const u16* Wn; ffn1_ptrs(p, l, next, An, Wn); gemm_issue(pf, An, 1024, Wn, 1024); }
.LBB1_246:
	s_mov_b32 s26, s16
	s_add_i32 s16, s16, s78
	s_cmpk_gt_i32 s16, 0x7ff
	s_cselect_b64 s[24:25], -1, 0
	s_cmpk_lt_i32 s16, 0x800
	v_mov_b32_e32 v148, v172
	v_mov_b32_e32 v0, v172
	s_cselect_b32 s0, s16, -1
	s_and_b32 s41, s40, 0x3f80
	s_and_b32 s27, s35, 0xfe0000
	v_ashrrev_i32_e32 v2, 1, v0
	v_add_u32_e32 v2, s41, v2
	v_ashrrev_i32_e32 v3, 31, v2
	v_lshlrev_b64 v[2:3], 6, v[2:3]
	v_lshlrev_b32_e32 v0, 5, v0
	v_lshl_add_u64 v[2:3], s[20:21], 0, v[2:3]
	v_and_b32_e32 v0, 32, v0
	v_lshl_add_u64 v[2:3], v[2:3], 0, v[0:1]
	global_load_dwordx4 v[66:69], v[2:3], off offset:16
	global_load_dwordx4 v[70:73], v[2:3], off
	s_and_b32 s26, s26, 0xffffff80
	s_lshl_b32 s26, s26, 1
	s_lshr_b32 s27, s27, 4
	s_add_u32 s28, s17, s27
	s_addc_u32 s29, s34, 0
	s_ashr_i32 s27, s26, 31
	s_lshl_b64 s[30:31], s[26:27], 6
	s_add_u32 s30, s36, s30
	s_addc_u32 s31, s37, s31
	s_setprio 0
	s_waitcnt lgkmcnt(0)
	s_mov_b32 s0, 0
	v_and_b32_e32 v149, 63, v172
	v_lshrrev_b32_e32 v151, 6, v172
	v_bfe_u32 v152, v149, 4, 2
	v_lshrrev_b32_e32 v153, 1, v152
	v_xor_b32_e32 v152, v152, v153
	v_and_b32_e32 v152, 1, v152
	v_lshl_or_b32 v152, v152, 1, v153
	v_xor_b32_e32 v152, v152, v149
	v_and_b32_e32 v152, 3, v152
	v_lshlrev_b32_e32 v152, 4, v152
	v_lshrrev_b32_e32 v153, 2, v149
	v_lshl_add_u32 v142, v151, 5, v153
	v_lshl_add_u32 v142, v142, 6, v152
	v_mov_b32_e32 v143, v142
	v_lshl_add_u32 v144, v151, 6, v153
	v_lshl_add_u32 v144, v144, 6, v152
	v_mov_b32_e32 v145, v144
	v_mov_b32_e32 v146, v144
	v_mov_b32_e32 v147, v144
	v_readfirstlane_b32 s42, v151
	s_lshl_b32 s43, s42, 12
	s_lshl_b32 s42, s42, 11
	s_add_u32 s43, s43, 0x2000
	v_bfe_u32 v152, v149, 2, 2
	v_lshrrev_b32_e32 v153, 1, v152
	v_xor_b32_e32 v152, v152, v153
	v_and_b32_e32 v152, 1, v152
	v_lshl_or_b32 v152, v152, 1, v153
	v_lshrrev_b32_e32 v153, 4, v149
	v_xor_b32_e32 v152, v152, v153
	v_lshlrev_b32_e32 v152, 4, v152
	v_and_b32_e32 v149, 15, v149
	v_lshl_add_u32 v149, v149, 6, v152
	v_lshrrev_b32_e32 v152, 1, v151
	v_and_b32_e32 v153, 1, v151
	v_lshl_add_u32 v138, v152, 12, v149
	v_lshl_add_u32 v140, v153, 12, v149
	v_add_u32_e32 v140, 0x2000, v140
	s_barrier
	s_add_u32 m0, s42, 0x0
	s_nop 0
	global_load_lds_dwordx4 v142, s[28:29]
	global_load_lds_dwordx4 v143, s[28:29] offset:1024
	s_add_u32 m0, s43, 0x0
	s_nop 0
	global_load_lds_dwordx4 v144, s[30:31]
	global_load_lds_dwordx4 v145, s[30:31] offset:1024
	global_load_lds_dwordx4 v146, s[30:31] offset:2048
	global_load_lds_dwordx4 v147, s[30:31] offset:3072
	s_add_u32 m0, s42, 0x6000
	s_add_u32 s28, s28, 0x100000
	s_addc_u32 s29, s29, 0
	global_load_lds_dwordx4 v142, s[28:29]
	global_load_lds_dwordx4 v143, s[28:29] offset:1024
	s_add_u32 m0, s43, 0x6000
	s_add_u32 s30, s30, 0x40000
	s_addc_u32 s31, s31, 0
	global_load_lds_dwordx4 v144, s[30:31]
	global_load_lds_dwordx4 v145, s[30:31] offset:1024
	global_load_lds_dwordx4 v146, s[30:31] offset:2048
	global_load_lds_dwordx4 v147, s[30:31] offset:3072
	s_waitcnt vmcnt(6)
	s_barrier
	ds_read_b128 v[208:211], v138 offset:0
	ds_read_b128 v[224:227], v140 offset:0
	ds_read_b128 v[228:231], v140 offset:1024
	ds_read_b128 v[232:235], v140 offset:2048
	ds_read_b128 v[236:239], v140 offset:3072
	s_add_u32 m0, s42, 0xc000
	s_add_u32 s28, s28, 0x100000
	s_addc_u32 s29, s29, 0
	global_load_lds_dwordx4 v142, s[28:29]
	global_load_lds_dwordx4 v143, s[28:29] offset:1024
	s_add_u32 m0, s43, 0xc000
	s_add_u32 s30, s30, 0x40000
	s_addc_u32 s31, s31, 0
	global_load_lds_dwordx4 v144, s[30:31]
	global_load_lds_dwordx4 v145, s[30:31] offset:1024
	global_load_lds_dwordx4 v146, s[30:31] offset:2048
	global_load_lds_dwordx4 v147, s[30:31] offset:3072
	ds_read_b128 v[212:215], v138 offset:1024
	ds_read_b128 v[216:219], v138 offset:2048
	ds_read_b128 v[220:223], v138 offset:3072
	ds_read_b128 v[240:243], v140 offset:8192
	ds_read_b128 v[244:247], v140 offset:9216
	ds_read_b128 v[248:251], v140 offset:10240
	ds_read_b128 v[156:159], v140 offset:11264
	s_waitcnt lgkmcnt(10)
	v_mfma_f32_16x16x32_bf16 v[2:5], v[224:227], v[208:211], 0
	s_waitcnt lgkmcnt(9)
	v_mfma_f32_16x16x32_bf16 v[6:9], v[228:231], v[208:211], 0
	s_waitcnt lgkmcnt(8)
	v_mfma_f32_16x16x32_bf16 v[10:13], v[232:235], v[208:211], 0
	s_waitcnt lgkmcnt(7)
	v_mfma_f32_16x16x32_bf16 v[14:17], v[236:239], v[208:211], 0
	s_waitcnt lgkmcnt(6)
	v_mfma_f32_16x16x32_bf16 v[18:21], v[224:227], v[212:215], 0
	v_mfma_f32_16x16x32_bf16 v[22:25], v[228:231], v[212:215], 0
	v_mfma_f32_16x16x32_bf16 v[26:29], v[232:235], v[212:215], 0
	v_mfma_f32_16x16x32_bf16 v[30:33], v[236:239], v[212:215], 0
	s_waitcnt lgkmcnt(5)
	v_mfma_f32_16x16x32_bf16 v[34:37], v[224:227], v[216:219], 0
	v_mfma_f32_16x16x32_bf16 v[38:41], v[228:231], v[216:219], 0
	v_mfma_f32_16x16x32_bf16 v[42:45], v[232:235], v[216:219], 0
	v_mfma_f32_16x16x32_bf16 v[46:49], v[236:239], v[216:219], 0
	s_waitcnt lgkmcnt(4)
	v_mfma_f32_16x16x32_bf16 v[50:53], v[224:227], v[220:223], 0
	v_mfma_f32_16x16x32_bf16 v[54:57], v[228:231], v[220:223], 0
	v_mfma_f32_16x16x32_bf16 v[58:61], v[232:235], v[220:223], 0
	v_mfma_f32_16x16x32_bf16 v[62:65], v[236:239], v[220:223], 0
	s_waitcnt lgkmcnt(3)
	v_mfma_f32_16x16x32_bf16 v[74:77], v[240:243], v[208:211], 0
	s_waitcnt lgkmcnt(2)
	v_mfma_f32_16x16x32_bf16 v[78:81], v[244:247], v[208:211], 0
	s_waitcnt lgkmcnt(1)
	v_mfma_f32_16x16x32_bf16 v[82:85], v[248:251], v[208:211], 0
	s_waitcnt lgkmcnt(0)
	v_mfma_f32_16x16x32_bf16 v[86:89], v[156:159], v[208:211], 0
	v_mfma_f32_16x16x32_bf16 v[90:93], v[240:243], v[212:215], 0
	v_mfma_f32_16x16x32_bf16 v[94:97], v[244:247], v[212:215], 0
	v_mfma_f32_16x16x32_bf16 v[98:101], v[248:251], v[212:215], 0
	v_mfma_f32_16x16x32_bf16 v[102:105], v[156:159], v[212:215], 0
	v_mfma_f32_16x16x32_bf16 v[106:109], v[240:243], v[216:219], 0
	v_mfma_f32_16x16x32_bf16 v[110:113], v[244:247], v[216:219], 0
	v_mfma_f32_16x16x32_bf16 v[114:117], v[248:251], v[216:219], 0
	v_mfma_f32_16x16x32_bf16 v[118:121], v[156:159], v[216:219], 0
	v_mfma_f32_16x16x32_bf16 v[122:125], v[240:243], v[220:223], 0
	v_mfma_f32_16x16x32_bf16 v[126:129], v[244:247], v[220:223], 0
	v_mfma_f32_16x16x32_bf16 v[130:133], v[248:251], v[220:223], 0
	v_mfma_f32_16x16x32_bf16 v[134:137], v[156:159], v[220:223], 0
	s_waitcnt vmcnt(6)
	s_barrier
; #define BLOAD(A_, B_, kt) do { _Pragma("unroll") for (int i = 0; i < 4; ++i) { \
;     A_[i] = *(const u32x4*)((const char*)Ap + (aoff + (unsigned)(32 * i * lda + (kt) * 64) * 2u)); B_[i] = *(const u32x4*)((const char*)Wt + (woff + (unsigned)(32 * i * K + (kt) * 64) * 2u)); } } while (0)
; #define BLOAD(A_, B_, kt) do { _Pragma("unroll") for (int i = 0; i < 4; ++i) { \
;     A_[i] = *(const u32x4*)((const char*)Ap + (aoff + (unsigned)(32 * i * lda + (kt) * 64) * 2u)); B_[i] = *(const u32x4*)((const char*)Wt + (woff + (unsigned)(32 * i * K + (kt) * 64) * 2u)); } } while (0)
; #define BSTORE(A_, B_, buf) do { _Pragma("unroll") for (int i = 0; i < 4; ++i) { \
;     *(u32x4*)&As[(buf) * GBUF + (srow + 32 * i) * LDT + sc8] = A_[i]; \
;     *(u32x4*)&Bs[(buf) * GBUF + (srow + 32 * i) * LDT + sc8] = B_[i]; } } while (0)
; template <int NK>
; DI void gemm_run(PF& pf, const u16* __restrict__ Ap, int lda, const u16* __restrict__ Wt, f32x16 (&acc)[2][2], char* smem) {
;     ...
; #pragma unroll
;   for (int kt = 0; kt < nk; kt += 2) {
;     BCOMP(0);
;     BSTORE(pf.a1, pf.b1, 1);
;     if (kt + 3 < nk) BLOAD(pf.a1, pf.b1, kt + 3);
;     __syncthreads();
;     BCOMP(1);
;     if (kt + 2 < nk) { BSTORE(pf.a0, pf.b0, 0); if (kt + 4 < nk) BLOAD(pf.a0, pf.b0, kt + 4); }
;     __syncthreads();
;   }
	ds_read_b128 v[208:211], v138 offset:24576
	ds_read_b128 v[224:227], v140 offset:24576
	ds_read_b128 v[228:231], v140 offset:25600
	ds_read_b128 v[232:235], v140 offset:26624
	ds_read_b128 v[236:239], v140 offset:27648
	s_add_u32 m0, s42, 0x0
	s_add_u32 s28, s28, 0x100000
	s_addc_u32 s29, s29, 0
	global_load_lds_dwordx4 v142, s[28:29]
	global_load_lds_dwordx4 v143, s[28:29] offset:1024
	s_add_u32 m0, s43, 0x0
	s_add_u32 s30, s30, 0x40000
	s_addc_u32 s31, s31, 0
	global_load_lds_dwordx4 v144, s[30:31]
	global_load_lds_dwordx4 v145, s[30:31] offset:1024
	global_load_lds_dwordx4 v146, s[30:31] offset:2048
	global_load_lds_dwordx4 v147, s[30:31] offset:3072
	ds_read_b128 v[212:215], v138 offset:25600
	ds_read_b128 v[216:219], v138 offset:26624
	ds_read_b128 v[220:223], v138 offset:27648
	ds_read_b128 v[240:243], v140 offset:32768
	ds_read_b128 v[244:247], v140 offset:33792
	ds_read_b128 v[248:251], v140 offset:34816
	ds_read_b128 v[156:159], v140 offset:35840
	s_waitcnt lgkmcnt(10)
	v_mfma_f32_16x16x32_bf16 v[2:5], v[224:227], v[208:211], v[2:5]
	s_waitcnt lgkmcnt(9)
	v_mfma_f32_16x16x32_bf16 v[6:9], v[228:231], v[208:211], v[6:9]
	s_waitcnt lgkmcnt(8)
	v_mfma_f32_16x16x32_bf16 v[10:13], v[232:235], v[208:211], v[10:13]
	s_waitcnt lgkmcnt(7)
	v_mfma_f32_16x16x32_bf16 v[14:17], v[236:239], v[208:211], v[14:17]
	s_waitcnt lgkmcnt(6)
	v_mfma_f32_16x16x32_bf16 v[18:21], v[224:227], v[212:215], v[18:21]
	v_mfma_f32_16x16x32_bf16 v[22:25], v[228:231], v[212:215], v[22:25]
	v_mfma_f32_16x16x32_bf16 v[26:29], v[232:235], v[212:215], v[26:29]
	v_mfma_f32_16x16x32_bf16 v[30:33], v[236:239], v[212:215], v[30:33]
	s_waitcnt lgkmcnt(5)
	v_mfma_f32_16x16x32_bf16 v[34:37], v[224:227], v[216:219], v[34:37]
	v_mfma_f32_16x16x32_bf16 v[38:41], v[228:231], v[216:219], v[38:41]
	v_mfma_f32_16x16x32_bf16 v[42:45], v[232:235], v[216:219], v[42:45]
	v_mfma_f32_16x16x32_bf16 v[46:49], v[236:239], v[216:219], v[46:49]
	s_waitcnt lgkmcnt(4)
	v_mfma_f32_16x16x32_bf16 v[50:53], v[224:227], v[220:223], v[50:53]
	v_mfma_f32_16x16x32_bf16 v[54:57], v[228:231], v[220:223], v[54:57]
	v_mfma_f32_16x16x32_bf16 v[58:61], v[232:235], v[220:223], v[58:61]
	v_mfma_f32_16x16x32_bf16 v[62:65], v[236:239], v[220:223], v[62:65]
	s_waitcnt lgkmcnt(3)
	v_mfma_f32_16x16x32_bf16 v[74:77], v[240:243], v[208:211], v[74:77]
	s_waitcnt lgkmcnt(2)
	v_mfma_f32_16x16x32_bf16 v[78:81], v[244:247], v[208:211], v[78:81]
	s_waitcnt lgkmcnt(1)
	v_mfma_f32_16x16x32_bf16 v[82:85], v[248:251], v[208:211], v[82:85]
	s_waitcnt lgkmcnt(0)
	v_mfma_f32_16x16x32_bf16 v[86:89], v[156:159], v[208:211], v[86:89]
	v_mfma_f32_16x16x32_bf16 v[90:93], v[240:243], v[212:215], v[90:93]
	v_mfma_f32_16x16x32_bf16 v[94:97], v[244:247], v[212:215], v[94:97]
	v_mfma_f32_16x16x32_bf16 v[98:101], v[248:251], v[212:215], v[98:101]
	v_mfma_f32_16x16x32_bf16 v[102:105], v[156:159], v[212:215], v[102:105]
	v_mfma_f32_16x16x32_bf16 v[106:109], v[240:243], v[216:219], v[106:109]
	v_mfma_f32_16x16x32_bf16 v[110:113], v[244:247], v[216:219], v[110:113]
	v_mfma_f32_16x16x32_bf16 v[114:117], v[248:251], v[216:219], v[114:117]
	v_mfma_f32_16x16x32_bf16 v[118:121], v[156:159], v[216:219], v[118:121]
	v_mfma_f32_16x16x32_bf16 v[122:125], v[240:243], v[220:223], v[122:125]
	v_mfma_f32_16x16x32_bf16 v[126:129], v[244:247], v[220:223], v[126:129]
	v_mfma_f32_16x16x32_bf16 v[130:133], v[248:251], v[220:223], v[130:133]
	v_mfma_f32_16x16x32_bf16 v[134:137], v[156:159], v[220:223], v[134:137]
	s_waitcnt vmcnt(6)
	s_barrier
	ds_read_b128 v[208:211], v138 offset:49152
	ds_read_b128 v[224:227], v140 offset:49152
	ds_read_b128 v[228:231], v140 offset:50176
	ds_read_b128 v[232:235], v140 offset:51200
	ds_read_b128 v[236:239], v140 offset:52224
	s_add_u32 m0, s42, 0x6000
	s_add_u32 s28, s28, 0x100000
	s_addc_u32 s29, s29, 0
	global_load_lds_dwordx4 v142, s[28:29]
	global_load_lds_dwordx4 v143, s[28:29] offset:1024
	s_add_u32 m0, s43, 0x6000
	s_add_u32 s30, s30, 0x40000
	s_addc_u32 s31, s31, 0
	global_load_lds_dwordx4 v144, s[30:31]
	global_load_lds_dwordx4 v145, s[30:31] offset:1024
	global_load_lds_dwordx4 v146, s[30:31] offset:2048
	global_load_lds_dwordx4 v147, s[30:31] offset:3072
	ds_read_b128 v[212:215], v138 offset:50176
	ds_read_b128 v[216:219], v138 offset:51200
	ds_read_b128 v[220:223], v138 offset:52224
	ds_read_b128 v[240:243], v140 offset:57344
	ds_read_b128 v[244:247], v140 offset:58368
	ds_read_b128 v[248:251], v140 offset:59392
	ds_read_b128 v[156:159], v140 offset:60416
	s_waitcnt lgkmcnt(10)
	v_mfma_f32_16x16x32_bf16 v[2:5], v[224:227], v[208:211], v[2:5]
	s_waitcnt lgkmcnt(9)
	v_mfma_f32_16x16x32_bf16 v[6:9], v[228:231], v[208:211], v[6:9]
	s_waitcnt lgkmcnt(8)
	v_mfma_f32_16x16x32_bf16 v[10:13], v[232:235], v[208:211], v[10:13]
	s_waitcnt lgkmcnt(7)
	v_mfma_f32_16x16x32_bf16 v[14:17], v[236:239], v[208:211], v[14:17]
	s_waitcnt lgkmcnt(6)
	v_mfma_f32_16x16x32_bf16 v[18:21], v[224:227], v[212:215], v[18:21]
	v_mfma_f32_16x16x32_bf16 v[22:25], v[228:231], v[212:215], v[22:25]
	v_mfma_f32_16x16x32_bf16 v[26:29], v[232:235], v[212:215], v[26:29]
	v_mfma_f32_16x16x32_bf16 v[30:33], v[236:239], v[212:215], v[30:33]
	s_waitcnt lgkmcnt(5)
	v_mfma_f32_16x16x32_bf16 v[34:37], v[224:227], v[216:219], v[34:37]
	v_mfma_f32_16x16x32_bf16 v[38:41], v[228:231], v[216:219], v[38:41]
	v_mfma_f32_16x16x32_bf16 v[42:45], v[232:235], v[216:219], v[42:45]
	v_mfma_f32_16x16x32_bf16 v[46:49], v[236:239], v[216:219], v[46:49]
	s_waitcnt lgkmcnt(4)
	v_mfma_f32_16x16x32_bf16 v[50:53], v[224:227], v[220:223], v[50:53]
	v_mfma_f32_16x16x32_bf16 v[54:57], v[228:231], v[220:223], v[54:57]
	v_mfma_f32_16x16x32_bf16 v[58:61], v[232:235], v[220:223], v[58:61]
	v_mfma_f32_16x16x32_bf16 v[62:65], v[236:239], v[220:223], v[62:65]
	s_waitcnt lgkmcnt(3)
	v_mfma_f32_16x16x32_bf16 v[74:77], v[240:243], v[208:211], v[74:77]
	s_waitcnt lgkmcnt(2)
	v_mfma_f32_16x16x32_bf16 v[78:81], v[244:247], v[208:211], v[78:81]
	s_waitcnt lgkmcnt(1)
	v_mfma_f32_16x16x32_bf16 v[82:85], v[248:251], v[208:211], v[82:85]
	s_waitcnt lgkmcnt(0)
	v_mfma_f32_16x16x32_bf16 v[86:89], v[156:159], v[208:211], v[86:89]
	v_mfma_f32_16x16x32_bf16 v[90:93], v[240:243], v[212:215], v[90:93]
	v_mfma_f32_16x16x32_bf16 v[94:97], v[244:247], v[212:215], v[94:97]
	v_mfma_f32_16x16x32_bf16 v[98:101], v[248:251], v[212:215], v[98:101]
	v_mfma_f32_16x16x32_bf16 v[102:105], v[156:159], v[212:215], v[102:105]
	v_mfma_f32_16x16x32_bf16 v[106:109], v[240:243], v[216:219], v[106:109]
	v_mfma_f32_16x16x32_bf16 v[110:113], v[244:247], v[216:219], v[110:113]
	v_mfma_f32_16x16x32_bf16 v[114:117], v[248:251], v[216:219], v[114:117]
	v_mfma_f32_16x16x32_bf16 v[118:121], v[156:159], v[216:219], v[118:121]
	v_mfma_f32_16x16x32_bf16 v[122:125], v[240:243], v[220:223], v[122:125]
	v_mfma_f32_16x16x32_bf16 v[126:129], v[244:247], v[220:223], v[126:129]
	v_mfma_f32_16x16x32_bf16 v[130:133], v[248:251], v[220:223], v[130:133]
	v_mfma_f32_16x16x32_bf16 v[134:137], v[156:159], v[220:223], v[134:137]
	s_mov_b32 s46, 9
	.p2align 6

; DI int TID() { int t = (int)__builtin_amdgcn_workitem_id_x(); asm volatile("" : "+v"(t)); return t; }
; #define BLOAD(A_, B_, kt) do { _Pragma("unroll") for (int i = 0; i < 4; ++i) { \
;     A_[i] = *(const u32x4*)((const char*)Ap + (aoff + (unsigned)(32 * i * lda + (kt) * 64) * 2u)); B_[i] = *(const u32x4*)((const char*)Wt + (woff + (unsigned)(32 * i * K + (kt) * 64) * 2u)); } } while (0)
; #define BLOAD(A_, B_, kt) do { _Pragma("unroll") for (int i = 0; i < 4; ++i) { \
;     A_[i] = *(const u32x4*)((const char*)Ap + (aoff + (unsigned)(32 * i * lda + (kt) * 64) * 2u)); B_[i] = *(const u32x4*)((const char*)Wt + (woff + (unsigned)(32 * i * K + (kt) * 64) * 2u)); } } while (0)
; template <int NK>
; DI void gemm_run(PF& pf, const u16* __restrict__ Ap, int lda, const u16* __restrict__ Wt, f32x16 (&acc)[2][2], char* smem) {
;   constexpr int K = NK * 64;
;   const int tid = TID(), lane = tid & 63, w = tid >> 6, wm = w >> 1, wn = w & 1, r32 = lane & 31, hi = lane >> 5;
;   u16* As = (u16*)smem; u16* Bs = As + 128 * LDT;
;   const int srow = tid >> 3, sc8 = (tid & 7) * 8;
;   constexpr int nk = NK;
;   const unsigned aoff = (unsigned)(srow * lda + sc8) * 2u, woff = (unsigned)(srow * K + sc8) * 2u;
;     ...
;   __builtin_amdgcn_s_setprio(0);
;   __syncthreads();
;   BSTORE(pf.a0, pf.b0, 0);
;   BLOAD(pf.a0, pf.b0, 2);
;   __syncthreads();
; #pragma unroll
;   for (int kt = 0; kt < nk; kt += 2) {
;     BCOMP(0);
;     BSTORE(pf.a1, pf.b1, 1);
;     if (kt + 3 < nk) BLOAD(pf.a1, pf.b1, kt + 3);
;     __syncthreads();
;     BCOMP(1);
;     if (kt + 2 < nk) { BSTORE(pf.a0, pf.b0, 0); if (kt + 4 < nk) BLOAD(pf.a0, pf.b0, kt + 4); }
;     __syncthreads();
;   }
; DI void tile_outproj(const Params& p, int l, const Chunk& ck, int tile, int next, PF& pf, char* smem) {
;   float* Cs = (float*)smem;
;   const int tid = TID(); const int mi = tile & (MTN - 1), ni = tile >> MTS; const int m0 = mi * 128, n0 = ni * 128;
;   f32x16 acc[2][2]; zero_acc(acc);
;   { const u16* Ap; const u16* Wt; outproj_ptrs(p, l, tile, Ap, Wt); gemm_run<16>(pf, Ap, 1024, Wt, acc, smem); }
;   if (next >= 0) { const u16* An; const u16* Wn; outproj_ptrs(p, l, next, An, Wn); gemm_issue(pf, An, 1024, Wn, 1024); }
.LBB1_255:
	s_add_i32 s41, s35, s78
	s_cmpk_gt_i32 s41, 0x1ff
	s_cselect_b64 s[24:25], -1, 0
	s_cmpk_lt_i32 s41, 0x200
	s_cselect_b32 s0, s41, -1
	s_and_b32 s27, s34, 0xfe0000
	s_and_b32 s26, s35, 0xffffff80
	s_lshl_b32 s26, s26, 1
	s_lshr_b32 s27, s27, 4
	s_add_u32 s28, s16, s27
	v_mov_b32_e32 v0, v172
	s_addc_u32 s29, s17, 0
	s_ashr_i32 s27, s26, 31
	s_lshl_b64 s[30:31], s[26:27], 6
	s_add_u32 s30, s36, s30
	s_addc_u32 s31, s37, s31
	s_setprio 0
	s_waitcnt lgkmcnt(0)
	v_and_b32_e32 v150, 63, v172
	v_lshrrev_b32_e32 v151, 6, v172
	v_bfe_u32 v152, v150, 4, 2
	v_lshrrev_b32_e32 v153, 1, v152
	v_xor_b32_e32 v152, v152, v153
	v_and_b32_e32 v152, 1, v152
	v_lshl_or_b32 v152, v152, 1, v153
	v_xor_b32_e32 v152, v152, v150
	v_and_b32_e32 v152, 3, v152
	v_lshlrev_b32_e32 v152, 4, v152
	v_lshrrev_b32_e32 v153, 2, v150
	v_lshl_add_u32 v143, v151, 5, v153
	v_lshl_add_u32 v143, v143, 6, v152
	v_mov_b32_e32 v144, v143
	v_lshl_add_u32 v145, v151, 6, v153
	v_lshl_add_u32 v145, v145, 6, v152
	v_mov_b32_e32 v146, v145
	v_mov_b32_e32 v147, v145
	v_mov_b32_e32 v148, v145
	v_readfirstlane_b32 s42, v151
	s_lshl_b32 s43, s42, 12
	s_lshl_b32 s42, s42, 11
	s_add_u32 s43, s43, 0x2000
	v_bfe_u32 v152, v150, 2, 2
	v_lshrrev_b32_e32 v153, 1, v152
	v_xor_b32_e32 v152, v152, v153
	v_and_b32_e32 v152, 1, v152
	v_lshl_or_b32 v152, v152, 1, v153
	v_lshrrev_b32_e32 v153, 4, v150
	v_xor_b32_e32 v152, v152, v153
	v_lshlrev_b32_e32 v152, 4, v152
	v_and_b32_e32 v150, 15, v150
	v_lshl_add_u32 v150, v150, 6, v152
	v_lshrrev_b32_e32 v152, 1, v151
	v_and_b32_e32 v153, 1, v151
	v_lshl_add_u32 v126, v152, 12, v150
	v_lshl_add_u32 v128, v153, 12, v150
	v_add_u32_e32 v128, 0x2000, v128
	s_barrier
	s_add_u32 m0, s42, 0x0
	s_nop 0
	global_load_lds_dwordx4 v143, s[28:29]
	global_load_lds_dwordx4 v144, s[28:29] offset:1024
	s_add_u32 m0, s43, 0x0
	s_nop 0
	global_load_lds_dwordx4 v145, s[30:31]
	global_load_lds_dwordx4 v146, s[30:31] offset:1024
	global_load_lds_dwordx4 v147, s[30:31] offset:2048
	global_load_lds_dwordx4 v148, s[30:31] offset:3072
	s_add_u32 m0, s42, 0x6000
	s_add_u32 s28, s28, 0x100000
	s_addc_u32 s29, s29, 0
	global_load_lds_dwordx4 v143, s[28:29]
	global_load_lds_dwordx4 v144, s[28:29] offset:1024
	s_add_u32 m0, s43, 0x6000
	s_add_u32 s30, s30, 0x10000
	s_addc_u32 s31, s31, 0
	global_load_lds_dwordx4 v145, s[30:31]
	global_load_lds_dwordx4 v146, s[30:31] offset:1024
	global_load_lds_dwordx4 v147, s[30:31] offset:2048
	global_load_lds_dwordx4 v148, s[30:31] offset:3072
	s_waitcnt vmcnt(6)
	s_barrier
	ds_read_b128 v[224:227], v126 offset:0
	ds_read_b128 v[240:243], v128 offset:0
	ds_read_b128 v[244:247], v128 offset:1024
	ds_read_b128 v[248:251], v128 offset:2048
	ds_read_b128 v[156:159], v128 offset:3072
	s_add_u32 m0, s42, 0xc000
	s_add_u32 s28, s28, 0x100000
	s_addc_u32 s29, s29, 0
	global_load_lds_dwordx4 v143, s[28:29]
	global_load_lds_dwordx4 v144, s[28:29] offset:1024
	s_add_u32 m0, s43, 0xc000
	s_add_u32 s30, s30, 0x10000
	s_addc_u32 s31, s31, 0
	global_load_lds_dwordx4 v145, s[30:31]
	global_load_lds_dwordx4 v146, s[30:31] offset:1024
	global_load_lds_dwordx4 v147, s[30:31] offset:2048
	global_load_lds_dwordx4 v148, s[30:31] offset:3072
	ds_read_b128 v[228:231], v126 offset:1024
	ds_read_b128 v[232:235], v126 offset:2048
	ds_read_b128 v[236:239], v126 offset:3072
	ds_read_b128 v[160:163], v128 offset:8192
	ds_read_b128 v[164:167], v128 offset:9216
	ds_read_b128 v[168:171], v128 offset:10240
	ds_read_b128 v[122:125], v128 offset:11264
	s_waitcnt lgkmcnt(10)
	v_mfma_f32_16x16x32_bf16 v[2:5], v[240:243], v[224:227], 0
	s_waitcnt lgkmcnt(9)
	v_mfma_f32_16x16x32_bf16 v[6:9], v[244:247], v[224:227], 0
	s_waitcnt lgkmcnt(8)
	v_mfma_f32_16x16x32_bf16 v[10:13], v[248:251], v[224:227], 0
	s_waitcnt lgkmcnt(7)
	v_mfma_f32_16x16x32_bf16 v[14:17], v[156:159], v[224:227], 0
	s_waitcnt lgkmcnt(6)
	v_mfma_f32_16x16x32_bf16 v[18:21], v[240:243], v[228:231], 0
	v_mfma_f32_16x16x32_bf16 v[22:25], v[244:247], v[228:231], 0
	v_mfma_f32_16x16x32_bf16 v[26:29], v[248:251], v[228:231], 0
	v_mfma_f32_16x16x32_bf16 v[30:33], v[156:159], v[228:231], 0
	s_waitcnt lgkmcnt(5)
	v_mfma_f32_16x16x32_bf16 v[34:37], v[240:243], v[232:235], 0
	v_mfma_f32_16x16x32_bf16 v[38:41], v[244:247], v[232:235], 0
	v_mfma_f32_16x16x32_bf16 v[42:45], v[248:251], v[232:235], 0
	v_mfma_f32_16x16x32_bf16 v[46:49], v[156:159], v[232:235], 0
	s_waitcnt lgkmcnt(4)
	v_mfma_f32_16x16x32_bf16 v[50:53], v[240:243], v[236:239], 0
	v_mfma_f32_16x16x32_bf16 v[54:57], v[244:247], v[236:239], 0
	v_mfma_f32_16x16x32_bf16 v[58:61], v[248:251], v[236:239], 0
	v_mfma_f32_16x16x32_bf16 v[62:65], v[156:159], v[236:239], 0
	s_waitcnt lgkmcnt(3)
	v_mfma_f32_16x16x32_bf16 v[74:77], v[160:163], v[224:227], 0
	s_waitcnt lgkmcnt(2)
	v_mfma_f32_16x16x32_bf16 v[78:81], v[164:167], v[224:227], 0
	s_waitcnt lgkmcnt(1)
	v_mfma_f32_16x16x32_bf16 v[82:85], v[168:171], v[224:227], 0
	s_waitcnt lgkmcnt(0)
	v_mfma_f32_16x16x32_bf16 v[86:89], v[122:125], v[224:227], 0
	v_mfma_f32_16x16x32_bf16 v[90:93], v[160:163], v[228:231], 0
	v_mfma_f32_16x16x32_bf16 v[94:97], v[164:167], v[228:231], 0
	v_mfma_f32_16x16x32_bf16 v[98:101], v[168:171], v[228:231], 0
	v_mfma_f32_16x16x32_bf16 v[102:105], v[122:125], v[228:231], 0
	v_mfma_f32_16x16x32_bf16 v[106:109], v[160:163], v[232:235], 0
	v_mfma_f32_16x16x32_bf16 v[110:113], v[164:167], v[232:235], 0
	v_mfma_f32_16x16x32_bf16 v[114:117], v[168:171], v[232:235], 0
	v_mfma_f32_16x16x32_bf16 v[118:121], v[122:125], v[232:235], 0
	v_mfma_f32_16x16x32_bf16 v[208:211], v[160:163], v[236:239], 0
	v_mfma_f32_16x16x32_bf16 v[212:215], v[164:167], v[236:239], 0
	v_mfma_f32_16x16x32_bf16 v[216:219], v[168:171], v[236:239], 0
	v_mfma_f32_16x16x32_bf16 v[220:223], v[122:125], v[236:239], 0
	s_waitcnt vmcnt(6)
	s_barrier
; #define BLOAD(A_, B_, kt) do { _Pragma("unroll") for (int i = 0; i < 4; ++i) { \
;     A_[i] = *(const u32x4*)((const char*)Ap + (aoff + (unsigned)(32 * i * lda + (kt) * 64) * 2u)); B_[i] = *(const u32x4*)((const char*)Wt + (woff + (unsigned)(32 * i * K + (kt) * 64) * 2u)); } } while (0)
; #define BLOAD(A_, B_, kt) do { _Pragma("unroll") for (int i = 0; i < 4; ++i) { \
;     A_[i] = *(const u32x4*)((const char*)Ap + (aoff + (unsigned)(32 * i * lda + (kt) * 64) * 2u)); B_[i] = *(const u32x4*)((const char*)Wt + (woff + (unsigned)(32 * i * K + (kt) * 64) * 2u)); } } while (0)
; #define BSTORE(A_, B_, buf) do { _Pragma("unroll") for (int i = 0; i < 4; ++i) { \
;     *(u32x4*)&As[(buf) * GBUF + (srow + 32 * i) * LDT + sc8] = A_[i]; \
;     *(u32x4*)&Bs[(buf) * GBUF + (srow + 32 * i) * LDT + sc8] = B_[i]; } } while (0)
; template <int NK>
; DI void gemm_run(PF& pf, const u16* __restrict__ Ap, int lda, const u16* __restrict__ Wt, f32x16 (&acc)[2][2], char* smem) {
;     ...
;   __builtin_amdgcn_s_setprio(0);
;   __syncthreads();
;   BSTORE(pf.a0, pf.b0, 0);
;   BLOAD(pf.a0, pf.b0, 2);
;   __syncthreads();
; #pragma unroll
;   for (int kt = 0; kt < nk; kt += 2) {
;     BCOMP(0);
;     BSTORE(pf.a1, pf.b1, 1);
;     if (kt + 3 < nk) BLOAD(pf.a1, pf.b1, kt + 3);
;     __syncthreads();
;     BCOMP(1);
;     if (kt + 2 < nk) { BSTORE(pf.a0, pf.b0, 0); if (kt + 4 < nk) BLOAD(pf.a0, pf.b0, kt + 4); }
;     __syncthreads();
;   }
	ds_read_b128 v[224:227], v126 offset:24576
	ds_read_b128 v[240:243], v128 offset:24576
	ds_read_b128 v[244:247], v128 offset:25600
	ds_read_b128 v[248:251], v128 offset:26624
	ds_read_b128 v[156:159], v128 offset:27648
	s_add_u32 m0, s42, 0x0
	s_add_u32 s28, s28, 0x100000
	s_addc_u32 s29, s29, 0
	global_load_lds_dwordx4 v143, s[28:29]
	global_load_lds_dwordx4 v144, s[28:29] offset:1024
	s_add_u32 m0, s43, 0x0
	s_add_u32 s30, s30, 0x10000
	s_addc_u32 s31, s31, 0
	global_load_lds_dwordx4 v145, s[30:31]
	global_load_lds_dwordx4 v146, s[30:31] offset:1024
	global_load_lds_dwordx4 v147, s[30:31] offset:2048
	global_load_lds_dwordx4 v148, s[30:31] offset:3072
	ds_read_b128 v[228:231], v126 offset:25600
	ds_read_b128 v[232:235], v126 offset:26624
	ds_read_b128 v[236:239], v126 offset:27648
	ds_read_b128 v[160:163], v128 offset:32768
	ds_read_b128 v[164:167], v128 offset:33792
	ds_read_b128 v[168:171], v128 offset:34816
	ds_read_b128 v[122:125], v128 offset:35840
	s_waitcnt lgkmcnt(10)
	v_mfma_f32_16x16x32_bf16 v[2:5], v[240:243], v[224:227], v[2:5]
	s_waitcnt lgkmcnt(9)
	v_mfma_f32_16x16x32_bf16 v[6:9], v[244:247], v[224:227], v[6:9]
	s_waitcnt lgkmcnt(8)
	v_mfma_f32_16x16x32_bf16 v[10:13], v[248:251], v[224:227], v[10:13]
	s_waitcnt lgkmcnt(7)
	v_mfma_f32_16x16x32_bf16 v[14:17], v[156:159], v[224:227], v[14:17]
	s_waitcnt lgkmcnt(6)
	v_mfma_f32_16x16x32_bf16 v[18:21], v[240:243], v[228:231], v[18:21]
	v_mfma_f32_16x16x32_bf16 v[22:25], v[244:247], v[228:231], v[22:25]
	v_mfma_f32_16x16x32_bf16 v[26:29], v[248:251], v[228:231], v[26:29]
	v_mfma_f32_16x16x32_bf16 v[30:33], v[156:159], v[228:231], v[30:33]
	s_waitcnt lgkmcnt(5)
	v_mfma_f32_16x16x32_bf16 v[34:37], v[240:243], v[232:235], v[34:37]
	v_mfma_f32_16x16x32_bf16 v[38:41], v[244:247], v[232:235], v[38:41]
	v_mfma_f32_16x16x32_bf16 v[42:45], v[248:251], v[232:235], v[42:45]
	v_mfma_f32_16x16x32_bf16 v[46:49], v[156:159], v[232:235], v[46:49]
	s_waitcnt lgkmcnt(4)
	v_mfma_f32_16x16x32_bf16 v[50:53], v[240:243], v[236:239], v[50:53]
	v_mfma_f32_16x16x32_bf16 v[54:57], v[244:247], v[236:239], v[54:57]
	v_mfma_f32_16x16x32_bf16 v[58:61], v[248:251], v[236:239], v[58:61]
	v_mfma_f32_16x16x32_bf16 v[62:65], v[156:159], v[236:239], v[62:65]
	s_waitcnt lgkmcnt(3)
	v_mfma_f32_16x16x32_bf16 v[74:77], v[160:163], v[224:227], v[74:77]
	s_waitcnt lgkmcnt(2)
	v_mfma_f32_16x16x32_bf16 v[78:81], v[164:167], v[224:227], v[78:81]
	s_waitcnt lgkmcnt(1)
	v_mfma_f32_16x16x32_bf16 v[82:85], v[168:171], v[224:227], v[82:85]
	s_waitcnt lgkmcnt(0)
	v_mfma_f32_16x16x32_bf16 v[86:89], v[122:125], v[224:227], v[86:89]
	v_mfma_f32_16x16x32_bf16 v[90:93], v[160:163], v[228:231], v[90:93]
	v_mfma_f32_16x16x32_bf16 v[94:97], v[164:167], v[228:231], v[94:97]
	v_mfma_f32_16x16x32_bf16 v[98:101], v[168:171], v[228:231], v[98:101]
	v_mfma_f32_16x16x32_bf16 v[102:105], v[122:125], v[228:231], v[102:105]
	v_mfma_f32_16x16x32_bf16 v[106:109], v[160:163], v[232:235], v[106:109]
	v_mfma_f32_16x16x32_bf16 v[110:113], v[164:167], v[232:235], v[110:113]
	v_mfma_f32_16x16x32_bf16 v[114:117], v[168:171], v[232:235], v[114:117]
	v_mfma_f32_16x16x32_bf16 v[118:121], v[122:125], v[232:235], v[118:121]
	v_mfma_f32_16x16x32_bf16 v[208:211], v[160:163], v[236:239], v[208:211]
	v_mfma_f32_16x16x32_bf16 v[212:215], v[164:167], v[236:239], v[212:215]
	v_mfma_f32_16x16x32_bf16 v[216:219], v[168:171], v[236:239], v[216:219]
	v_mfma_f32_16x16x32_bf16 v[220:223], v[122:125], v[236:239], v[220:223]
	s_waitcnt vmcnt(6)
	s_barrier
	ds_read_b128 v[224:227], v126 offset:49152
	ds_read_b128 v[240:243], v128 offset:49152
	ds_read_b128 v[244:247], v128 offset:50176
	ds_read_b128 v[248:251], v128 offset:51200
	ds_read_b128 v[156:159], v128 offset:52224
	s_add_u32 m0, s42, 0x6000
	s_add_u32 s28, s28, 0x100000
	s_addc_u32 s29, s29, 0
	global_load_lds_dwordx4 v143, s[28:29]
	global_load_lds_dwordx4 v144, s[28:29] offset:1024
	s_add_u32 m0, s43, 0x6000
	s_add_u32 s30, s30, 0x10000
	s_addc_u32 s31, s31, 0
	global_load_lds_dwordx4 v145, s[30:31]
	global_load_lds_dwordx4 v146, s[30:31] offset:1024
	global_load_lds_dwordx4 v147, s[30:31] offset:2048
	global_load_lds_dwordx4 v148, s[30:31] offset:3072
	ds_read_b128 v[228:231], v126 offset:50176
	ds_read_b128 v[232:235], v126 offset:51200
	ds_read_b128 v[236:239], v126 offset:52224
	ds_read_b128 v[160:163], v128 offset:57344
	ds_read_b128 v[164:167], v128 offset:58368
	ds_read_b128 v[168:171], v128 offset:59392
	ds_read_b128 v[122:125], v128 offset:60416
	s_waitcnt lgkmcnt(10)
	v_mfma_f32_16x16x32_bf16 v[2:5], v[240:243], v[224:227], v[2:5]
	s_waitcnt lgkmcnt(9)
	v_mfma_f32_16x16x32_bf16 v[6:9], v[244:247], v[224:227], v[6:9]
	s_waitcnt lgkmcnt(8)
	v_mfma_f32_16x16x32_bf16 v[10:13], v[248:251], v[224:227], v[10:13]
	s_waitcnt lgkmcnt(7)
	v_mfma_f32_16x16x32_bf16 v[14:17], v[156:159], v[224:227], v[14:17]
	s_waitcnt lgkmcnt(6)
	v_mfma_f32_16x16x32_bf16 v[18:21], v[240:243], v[228:231], v[18:21]
	v_mfma_f32_16x16x32_bf16 v[22:25], v[244:247], v[228:231], v[22:25]
	v_mfma_f32_16x16x32_bf16 v[26:29], v[248:251], v[228:231], v[26:29]
	v_mfma_f32_16x16x32_bf16 v[30:33], v[156:159], v[228:231], v[30:33]
	s_waitcnt lgkmcnt(5)
	v_mfma_f32_16x16x32_bf16 v[34:37], v[240:243], v[232:235], v[34:37]
	v_mfma_f32_16x16x32_bf16 v[38:41], v[244:247], v[232:235], v[38:41]
	v_mfma_f32_16x16x32_bf16 v[42:45], v[248:251], v[232:235], v[42:45]
	v_mfma_f32_16x16x32_bf16 v[46:49], v[156:159], v[232:235], v[46:49]
	s_waitcnt lgkmcnt(4)
	v_mfma_f32_16x16x32_bf16 v[50:53], v[240:243], v[236:239], v[50:53]
	v_mfma_f32_16x16x32_bf16 v[54:57], v[244:247], v[236:239], v[54:57]
	v_mfma_f32_16x16x32_bf16 v[58:61], v[248:251], v[236:239], v[58:61]
	v_mfma_f32_16x16x32_bf16 v[62:65], v[156:159], v[236:239], v[62:65]
	s_waitcnt lgkmcnt(3)
	v_mfma_f32_16x16x32_bf16 v[74:77], v[160:163], v[224:227], v[74:77]
	s_waitcnt lgkmcnt(2)
	v_mfma_f32_16x16x32_bf16 v[78:81], v[164:167], v[224:227], v[78:81]
	s_waitcnt lgkmcnt(1)
	v_mfma_f32_16x16x32_bf16 v[82:85], v[168:171], v[224:227], v[82:85]
	s_waitcnt lgkmcnt(0)
	v_mfma_f32_16x16x32_bf16 v[86:89], v[122:125], v[224:227], v[86:89]
	v_mfma_f32_16x16x32_bf16 v[90:93], v[160:163], v[228:231], v[90:93]
	v_mfma_f32_16x16x32_bf16 v[94:97], v[164:167], v[228:231], v[94:97]
	v_mfma_f32_16x16x32_bf16 v[98:101], v[168:171], v[228:231], v[98:101]
	v_mfma_f32_16x16x32_bf16 v[102:105], v[122:125], v[228:231], v[102:105]
	v_mfma_f32_16x16x32_bf16 v[106:109], v[160:163], v[232:235], v[106:109]
	v_mfma_f32_16x16x32_bf16 v[110:113], v[164:167], v[232:235], v[110:113]
	v_mfma_f32_16x16x32_bf16 v[114:117], v[168:171], v[232:235], v[114:117]
	v_mfma_f32_16x16x32_bf16 v[118:121], v[122:125], v[232:235], v[118:121]
	v_mfma_f32_16x16x32_bf16 v[208:211], v[160:163], v[236:239], v[208:211]
	v_mfma_f32_16x16x32_bf16 v[212:215], v[164:167], v[236:239], v[212:215]
	v_mfma_f32_16x16x32_bf16 v[216:219], v[168:171], v[236:239], v[216:219]
	v_mfma_f32_16x16x32_bf16 v[220:223], v[122:125], v[236:239], v[220:223]
	s_mov_b32 s46, 9
	.p2align 6

; #define BLOAD(A_, B_, kt) do { _Pragma("unroll") for (int i = 0; i < 4; ++i) { \
;     A_[i] = *(const u32x4*)((const char*)Ap + (aoff + (unsigned)(32 * i * lda + (kt) * 64) * 2u)); B_[i] = *(const u32x4*)((const char*)Wt + (woff + (unsigned)(32 * i * K + (kt) * 64) * 2u)); } } while (0)
; #define BLOAD(A_, B_, kt) do { _Pragma("unroll") for (int i = 0; i < 4; ++i) { \
;     A_[i] = *(const u32x4*)((const char*)Ap + (aoff + (unsigned)(32 * i * lda + (kt) * 64) * 2u)); B_[i] = *(const u32x4*)((const char*)Wt + (woff + (unsigned)(32 * i * K + (kt) * 64) * 2u)); } } while (0)
; #define BSTORE(A_, B_, buf) do { _Pragma("unroll") for (int i = 0; i < 4; ++i) { \
;     *(u32x4*)&As[(buf) * GBUF + (srow + 32 * i) * LDT + sc8] = A_[i]; \
;     *(u32x4*)&Bs[(buf) * GBUF + (srow + 32 * i) * LDT + sc8] = B_[i]; } } while (0)
; template <bool ROWNORM, int NK>
; DI void gemm_main_bf(const u16* __restrict__ Ap, int lda, const u16* __restrict__ Wt, f32x16 (&acc)[2][2], char* smem, float* rinv_s) {
;     ...
;   __builtin_amdgcn_s_setprio(0);
;   BLOAD(a0, b0, 0); BLOAD(a1, b1, 1);
;   __syncthreads();
;   BSTORE(a0, b0, 0);
;   BLOAD(a0, b0, 2);
;   __syncthreads();
; #pragma unroll
;   for (int kt = 0; kt < nk; kt += 2) {
;     BCOMP(0);
;     BSTORE(a1, b1, 1);
;     if (kt + 3 < nk) BLOAD(a1, b1, kt + 3);
;     __syncthreads();
;     BCOMP(1);
;     if (kt + 2 < nk) { BSTORE(a0, b0, 0); if (kt + 4 < nk) BLOAD(a0, b0, kt + 4); }
;     __syncthreads();
;   }
; DI void tile_branch(const Params& p, int l, int tile, char* smem) {
;     ...
;       f32x16 accg[2][2]; zero_acc(accg);
;       gemm_main_bf<false, 16>((const u16*)(p.ws + OFF_XB) + (size_t)m0 * 1024, 1024,
;                               (const u16*)(p.ws + OFF_WIN + l * SZ_WIN) + (size_t)(5760 + br * 1024 + n0) * 1024, accg, smem, nullptr);
.Lbr_loop:
	s_waitcnt vmcnt(8)
	s_barrier
	ds_read_b128 v[208:211], v240 offset:0
	ds_read_b128 v[224:227], v241 offset:0
	ds_read_b128 v[228:231], v241 offset:1024
	ds_read_b128 v[232:235], v241 offset:2048
	ds_read_b128 v[236:239], v241 offset:3072
	s_add_u32 m0, s52, 0xc000
	s_add_u32 s28, s28, 0x100000
	s_addc_u32 s29, s29, 0
	global_load_lds_dwordx4 v251, s[28:29]
	global_load_lds_dwordx4 v251, s[28:29] offset:1024
	s_add_u32 m0, s53, 0xc000
	s_add_u32 s30, s30, 0x30000
	s_addc_u32 s31, s31, 0
	global_load_lds_dwordx4 v251, s[30:31]
	global_load_lds_dwordx4 v251, s[30:31] offset:1024
	ds_read_b128 v[212:215], v240 offset:1024
	ds_read_b128 v[216:219], v240 offset:2048
	ds_read_b128 v[220:223], v240 offset:3072
	s_waitcnt lgkmcnt(6)
	v_mfma_f32_16x16x32_bf16 v[2:5], v[224:227], v[208:211], 0
	s_waitcnt lgkmcnt(5)
	v_mfma_f32_16x16x32_bf16 v[6:9], v[228:231], v[208:211], 0
	s_waitcnt lgkmcnt(4)
	v_mfma_f32_16x16x32_bf16 v[10:13], v[232:235], v[208:211], 0
	s_waitcnt lgkmcnt(3)
	v_mfma_f32_16x16x32_bf16 v[14:17], v[236:239], v[208:211], 0
	s_waitcnt lgkmcnt(2)
	v_mfma_f32_16x16x32_bf16 v[18:21], v[224:227], v[212:215], 0
	v_mfma_f32_16x16x32_bf16 v[22:25], v[228:231], v[212:215], 0
	v_mfma_f32_16x16x32_bf16 v[26:29], v[232:235], v[212:215], 0
	v_mfma_f32_16x16x32_bf16 v[30:33], v[236:239], v[212:215], 0
	s_waitcnt lgkmcnt(1)
	v_mfma_f32_16x16x32_bf16 v[34:37], v[224:227], v[216:219], 0
	v_mfma_f32_16x16x32_bf16 v[38:41], v[228:231], v[216:219], 0
	v_mfma_f32_16x16x32_bf16 v[42:45], v[232:235], v[216:219], 0
	v_mfma_f32_16x16x32_bf16 v[46:49], v[236:239], v[216:219], 0
	s_waitcnt lgkmcnt(0)
	v_mfma_f32_16x16x32_bf16 v[50:53], v[224:227], v[220:223], 0
	v_mfma_f32_16x16x32_bf16 v[54:57], v[228:231], v[220:223], 0
	v_mfma_f32_16x16x32_bf16 v[58:61], v[232:235], v[220:223], 0
	v_mfma_f32_16x16x32_bf16 v[62:65], v[236:239], v[220:223], 0
	s_waitcnt vmcnt(8)
	s_barrier
	ds_read_b128 v[208:211], v240 offset:16384
	ds_read_b128 v[224:227], v241 offset:16384
	ds_read_b128 v[228:231], v241 offset:17408
	ds_read_b128 v[232:235], v241 offset:18432
	ds_read_b128 v[236:239], v241 offset:19456
	s_add_u32 m0, s52, 0x0
	s_add_u32 s28, s28, 0x100000
	s_addc_u32 s29, s29, 0
	global_load_lds_dwordx4 v251, s[28:29]
	global_load_lds_dwordx4 v251, s[28:29] offset:1024
	s_add_u32 m0, s53, 0x0
	s_add_u32 s30, s30, 0x30000
	s_addc_u32 s31, s31, 0
	global_load_lds_dwordx4 v251, s[30:31]
	global_load_lds_dwordx4 v251, s[30:31] offset:1024
	ds_read_b128 v[212:215], v240 offset:17408
	ds_read_b128 v[216:219], v240 offset:18432
	ds_read_b128 v[220:223], v240 offset:19456
	s_waitcnt lgkmcnt(6)
	v_mfma_f32_16x16x32_bf16 v[2:5], v[224:227], v[208:211], v[2:5]
	s_waitcnt lgkmcnt(5)
	v_mfma_f32_16x16x32_bf16 v[6:9], v[228:231], v[208:211], v[6:9]
	s_waitcnt lgkmcnt(4)
	v_mfma_f32_16x16x32_bf16 v[10:13], v[232:235], v[208:211], v[10:13]
	s_waitcnt lgkmcnt(3)
	v_mfma_f32_16x16x32_bf16 v[14:17], v[236:239], v[208:211], v[14:17]
	s_waitcnt lgkmcnt(2)
	v_mfma_f32_16x16x32_bf16 v[18:21], v[224:227], v[212:215], v[18:21]
	v_mfma_f32_16x16x32_bf16 v[22:25], v[228:231], v[212:215], v[22:25]
	v_mfma_f32_16x16x32_bf16 v[26:29], v[232:235], v[212:215], v[26:29]
	v_mfma_f32_16x16x32_bf16 v[30:33], v[236:239], v[212:215], v[30:33]
	s_waitcnt lgkmcnt(1)
	v_mfma_f32_16x16x32_bf16 v[34:37], v[224:227], v[216:219], v[34:37]
	v_mfma_f32_16x16x32_bf16 v[38:41], v[228:231], v[216:219], v[38:41]
	v_mfma_f32_16x16x32_bf16 v[42:45], v[232:235], v[216:219], v[42:45]
	v_mfma_f32_16x16x32_bf16 v[46:49], v[236:239], v[216:219], v[46:49]
	s_waitcnt lgkmcnt(0)
	v_mfma_f32_16x16x32_bf16 v[50:53], v[224:227], v[220:223], v[50:53]
	v_mfma_f32_16x16x32_bf16 v[54:57], v[228:231], v[220:223], v[54:57]
	v_mfma_f32_16x16x32_bf16 v[58:61], v[232:235], v[220:223], v[58:61]
	v_mfma_f32_16x16x32_bf16 v[62:65], v[236:239], v[220:223], v[62:65]
	s_waitcnt vmcnt(8)
	s_barrier
	ds_read_b128 v[208:211], v240 offset:32768
	ds_read_b128 v[224:227], v241 offset:32768
	ds_read_b128 v[228:231], v241 offset:33792
	ds_read_b128 v[232:235], v241 offset:34816
	ds_read_b128 v[236:239], v241 offset:35840
	s_add_u32 m0, s52, 0x4000
	s_add_u32 s28, s28, 0x100000
	s_addc_u32 s29, s29, 0
	global_load_lds_dwordx4 v251, s[28:29]
	global_load_lds_dwordx4 v251, s[28:29] offset:1024
	s_add_u32 m0, s53, 0x4000
	s_add_u32 s30, s30, 0x30000
	s_addc_u32 s31, s31, 0
	global_load_lds_dwordx4 v251, s[30:31]
	global_load_lds_dwordx4 v251, s[30:31] offset:1024
	ds_read_b128 v[212:215], v240 offset:33792
	ds_read_b128 v[216:219], v240 offset:34816
	ds_read_b128 v[220:223], v240 offset:35840
	s_waitcnt lgkmcnt(6)
	v_mfma_f32_16x16x32_bf16 v[2:5], v[224:227], v[208:211], v[2:5]
	s_waitcnt lgkmcnt(5)
	v_mfma_f32_16x16x32_bf16 v[6:9], v[228:231], v[208:211], v[6:9]
	s_waitcnt lgkmcnt(4)
	v_mfma_f32_16x16x32_bf16 v[10:13], v[232:235], v[208:211], v[10:13]
	s_waitcnt lgkmcnt(3)
	v_mfma_f32_16x16x32_bf16 v[14:17], v[236:239], v[208:211], v[14:17]
	s_waitcnt lgkmcnt(2)
	v_mfma_f32_16x16x32_bf16 v[18:21], v[224:227], v[212:215], v[18:21]
	v_mfma_f32_16x16x32_bf16 v[22:25], v[228:231], v[212:215], v[22:25]
	v_mfma_f32_16x16x32_bf16 v[26:29], v[232:235], v[212:215], v[26:29]
	v_mfma_f32_16x16x32_bf16 v[30:33], v[236:239], v[212:215], v[30:33]
	s_waitcnt lgkmcnt(1)
	v_mfma_f32_16x16x32_bf16 v[34:37], v[224:227], v[216:219], v[34:37]
	v_mfma_f32_16x16x32_bf16 v[38:41], v[228:231], v[216:219], v[38:41]
	v_mfma_f32_16x16x32_bf16 v[42:45], v[232:235], v[216:219], v[42:45]
	v_mfma_f32_16x16x32_bf16 v[46:49], v[236:239], v[216:219], v[46:49]
	s_waitcnt lgkmcnt(0)
	v_mfma_f32_16x16x32_bf16 v[50:53], v[224:227], v[220:223], v[50:53]
	v_mfma_f32_16x16x32_bf16 v[54:57], v[228:231], v[220:223], v[54:57]
	v_mfma_f32_16x16x32_bf16 v[58:61], v[232:235], v[220:223], v[58:61]
	v_mfma_f32_16x16x32_bf16 v[62:65], v[236:239], v[220:223], v[62:65]
	s_waitcnt vmcnt(8)
	s_barrier
; #define BLOAD(A_, B_, kt) do { _Pragma("unroll") for (int i = 0; i < 4; ++i) { \
;     A_[i] = *(const u32x4*)((const char*)Ap + (aoff + (unsigned)(32 * i * lda + (kt) * 64) * 2u)); B_[i] = *(const u32x4*)((const char*)Wt + (woff + (unsigned)(32 * i * K + (kt) * 64) * 2u)); } } while (0)
; #define BLOAD(A_, B_, kt) do { _Pragma("unroll") for (int i = 0; i < 4; ++i) { \
;     A_[i] = *(const u32x4*)((const char*)Ap + (aoff + (unsigned)(32 * i * lda + (kt) * 64) * 2u)); B_[i] = *(const u32x4*)((const char*)Wt + (woff + (unsigned)(32 * i * K + (kt) * 64) * 2u)); } } while (0)
; #define BSTORE(A_, B_, buf) do { _Pragma("unroll") for (int i = 0; i < 4; ++i) { \
;     *(u32x4*)&As[(buf) * GBUF + (srow + 32 * i) * LDT + sc8] = A_[i]; \
;     *(u32x4*)&Bs[(buf) * GBUF + (srow + 32 * i) * LDT + sc8] = B_[i]; } } while (0)
; template <bool ROWNORM, int NK>
; DI void gemm_main_bf(const u16* __restrict__ Ap, int lda, const u16* __restrict__ Wt, f32x16 (&acc)[2][2], char* smem, float* rinv_s) {
;     ...
;   __builtin_amdgcn_s_setprio(0);
;   BLOAD(a0, b0, 0); BLOAD(a1, b1, 1);
;   __syncthreads();
;   BSTORE(a0, b0, 0);
;   BLOAD(a0, b0, 2);
;   __syncthreads();
; #pragma unroll
;   for (int kt = 0; kt < nk; kt += 2) {
;     BCOMP(0);
;     BSTORE(a1, b1, 1);
;     if (kt + 3 < nk) BLOAD(a1, b1, kt + 3);
;     __syncthreads();
;     BCOMP(1);
;     if (kt + 2 < nk) { BSTORE(a0, b0, 0); if (kt + 4 < nk) BLOAD(a0, b0, kt + 4); }
;     __syncthreads();
;   }
	ds_read_b128 v[208:211], v240 offset:49152
	ds_read_b128 v[224:227], v241 offset:49152
	ds_read_b128 v[228:231], v241 offset:50176
	ds_read_b128 v[232:235], v241 offset:51200
	ds_read_b128 v[236:239], v241 offset:52224
	s_add_u32 m0, s52, 0x8000
	s_add_u32 s28, s28, 0x100000
	s_addc_u32 s29, s29, 0
	global_load_lds_dwordx4 v251, s[28:29]
	global_load_lds_dwordx4 v251, s[28:29] offset:1024
	s_add_u32 m0, s53, 0x8000
	s_add_u32 s30, s30, 0x30000
	s_addc_u32 s31, s31, 0
	global_load_lds_dwordx4 v251, s[30:31]
	global_load_lds_dwordx4 v251, s[30:31] offset:1024
	ds_read_b128 v[212:215], v240 offset:50176
	ds_read_b128 v[216:219], v240 offset:51200
	ds_read_b128 v[220:223], v240 offset:52224
	s_waitcnt lgkmcnt(6)
	v_mfma_f32_16x16x32_bf16 v[2:5], v[224:227], v[208:211], v[2:5]
	s_waitcnt lgkmcnt(5)
	v_mfma_f32_16x16x32_bf16 v[6:9], v[228:231], v[208:211], v[6:9]
	s_waitcnt lgkmcnt(4)
	v_mfma_f32_16x16x32_bf16 v[10:13], v[232:235], v[208:211], v[10:13]
	s_waitcnt lgkmcnt(3)
	v_mfma_f32_16x16x32_bf16 v[14:17], v[236:239], v[208:211], v[14:17]
	s_waitcnt lgkmcnt(2)
	v_mfma_f32_16x16x32_bf16 v[18:21], v[224:227], v[212:215], v[18:21]
	v_mfma_f32_16x16x32_bf16 v[22:25], v[228:231], v[212:215], v[22:25]
	v_mfma_f32_16x16x32_bf16 v[26:29], v[232:235], v[212:215], v[26:29]
	v_mfma_f32_16x16x32_bf16 v[30:33], v[236:239], v[212:215], v[30:33]
	s_waitcnt lgkmcnt(1)
	v_mfma_f32_16x16x32_bf16 v[34:37], v[224:227], v[216:219], v[34:37]
	v_mfma_f32_16x16x32_bf16 v[38:41], v[228:231], v[216:219], v[38:41]
	v_mfma_f32_16x16x32_bf16 v[42:45], v[232:235], v[216:219], v[42:45]
	v_mfma_f32_16x16x32_bf16 v[46:49], v[236:239], v[216:219], v[46:49]
	s_waitcnt lgkmcnt(0)
	v_mfma_f32_16x16x32_bf16 v[50:53], v[224:227], v[220:223], v[50:53]
	v_mfma_f32_16x16x32_bf16 v[54:57], v[228:231], v[220:223], v[54:57]
	v_mfma_f32_16x16x32_bf16 v[58:61], v[232:235], v[220:223], v[58:61]
	v_mfma_f32_16x16x32_bf16 v[62:65], v[236:239], v[220:223], v[62:65]
	s_mov_b32 s74, 6
	.p2align 6
.Lbr_gate_k:
	s_waitcnt vmcnt(8)
	s_barrier
	ds_read_b128 v[208:211], v240 offset:0
	ds_read_b128 v[224:227], v241 offset:0
	ds_read_b128 v[228:231], v241 offset:1024
	ds_read_b128 v[232:235], v241 offset:2048
	ds_read_b128 v[236:239], v241 offset:3072
	s_add_u32 m0, s52, 0xc000
	s_add_u32 s28, s28, 0x100000
	s_addc_u32 s29, s29, 0
	global_load_lds_dwordx4 v251, s[28:29]
	global_load_lds_dwordx4 v251, s[28:29] offset:1024
	s_add_u32 m0, s53, 0xc000
	s_add_u32 s30, s30, 0x30000
	s_addc_u32 s31, s31, 0
	global_load_lds_dwordx4 v251, s[30:31]
	global_load_lds_dwordx4 v251, s[30:31] offset:1024
	ds_read_b128 v[212:215], v240 offset:1024
	ds_read_b128 v[216:219], v240 offset:2048
	ds_read_b128 v[220:223], v240 offset:3072
	s_waitcnt lgkmcnt(6)
	v_mfma_f32_16x16x32_bf16 v[2:5], v[224:227], v[208:211], v[2:5]
	s_waitcnt lgkmcnt(5)
	v_mfma_f32_16x16x32_bf16 v[6:9], v[228:231], v[208:211], v[6:9]
	s_waitcnt lgkmcnt(4)
	v_mfma_f32_16x16x32_bf16 v[10:13], v[232:235], v[208:211], v[10:13]
	s_waitcnt lgkmcnt(3)
	v_mfma_f32_16x16x32_bf16 v[14:17], v[236:239], v[208:211], v[14:17]
	s_waitcnt lgkmcnt(2)
	v_mfma_f32_16x16x32_bf16 v[18:21], v[224:227], v[212:215], v[18:21]
	v_mfma_f32_16x16x32_bf16 v[22:25], v[228:231], v[212:215], v[22:25]
	v_mfma_f32_16x16x32_bf16 v[26:29], v[232:235], v[212:215], v[26:29]
	v_mfma_f32_16x16x32_bf16 v[30:33], v[236:239], v[212:215], v[30:33]
	s_waitcnt lgkmcnt(1)
	v_mfma_f32_16x16x32_bf16 v[34:37], v[224:227], v[216:219], v[34:37]
	v_mfma_f32_16x16x32_bf16 v[38:41], v[228:231], v[216:219], v[38:41]
	v_mfma_f32_16x16x32_bf16 v[42:45], v[232:235], v[216:219], v[42:45]
	v_mfma_f32_16x16x32_bf16 v[46:49], v[236:239], v[216:219], v[46:49]
	s_waitcnt lgkmcnt(0)
	v_mfma_f32_16x16x32_bf16 v[50:53], v[224:227], v[220:223], v[50:53]
	v_mfma_f32_16x16x32_bf16 v[54:57], v[228:231], v[220:223], v[54:57]
	v_mfma_f32_16x16x32_bf16 v[58:61], v[232:235], v[220:223], v[58:61]
	v_mfma_f32_16x16x32_bf16 v[62:65], v[236:239], v[220:223], v[62:65]
	s_waitcnt vmcnt(8)
	s_barrier
	ds_read_b128 v[208:211], v240 offset:16384
	ds_read_b128 v[224:227], v241 offset:16384
	ds_read_b128 v[228:231], v241 offset:17408
	ds_read_b128 v[232:235], v241 offset:18432
	ds_read_b128 v[236:239], v241 offset:19456
	s_add_u32 m0, s52, 0x0
	s_add_u32 s28, s28, 0x100000
	s_addc_u32 s29, s29, 0
	global_load_lds_dwordx4 v251, s[28:29]
	global_load_lds_dwordx4 v251, s[28:29] offset:1024
	s_add_u32 m0, s53, 0x0
	s_add_u32 s30, s30, 0x30000
	s_addc_u32 s31, s31, 0
	global_load_lds_dwordx4 v251, s[30:31]
	global_load_lds_dwordx4 v251, s[30:31] offset:1024
	ds_read_b128 v[212:215], v240 offset:17408
	ds_read_b128 v[216:219], v240 offset:18432
	ds_read_b128 v[220:223], v240 offset:19456
	s_waitcnt lgkmcnt(6)
	v_mfma_f32_16x16x32_bf16 v[2:5], v[224:227], v[208:211], v[2:5]
	s_waitcnt lgkmcnt(5)
	v_mfma_f32_16x16x32_bf16 v[6:9], v[228:231], v[208:211], v[6:9]
	s_waitcnt lgkmcnt(4)
	v_mfma_f32_16x16x32_bf16 v[10:13], v[232:235], v[208:211], v[10:13]
	s_waitcnt lgkmcnt(3)
	v_mfma_f32_16x16x32_bf16 v[14:17], v[236:239], v[208:211], v[14:17]
	s_waitcnt lgkmcnt(2)
	v_mfma_f32_16x16x32_bf16 v[18:21], v[224:227], v[212:215], v[18:21]
	v_mfma_f32_16x16x32_bf16 v[22:25], v[228:231], v[212:215], v[22:25]
	v_mfma_f32_16x16x32_bf16 v[26:29], v[232:235], v[212:215], v[26:29]
	v_mfma_f32_16x16x32_bf16 v[30:33], v[236:239], v[212:215], v[30:33]
	s_waitcnt lgkmcnt(1)
	v_mfma_f32_16x16x32_bf16 v[34:37], v[224:227], v[216:219], v[34:37]
	v_mfma_f32_16x16x32_bf16 v[38:41], v[228:231], v[216:219], v[38:41]
	v_mfma_f32_16x16x32_bf16 v[42:45], v[232:235], v[216:219], v[42:45]
	v_mfma_f32_16x16x32_bf16 v[46:49], v[236:239], v[216:219], v[46:49]
	s_waitcnt lgkmcnt(0)
	v_mfma_f32_16x16x32_bf16 v[50:53], v[224:227], v[220:223], v[50:53]
	v_mfma_f32_16x16x32_bf16 v[54:57], v[228:231], v[220:223], v[54:57]
	v_mfma_f32_16x16x32_bf16 v[58:61], v[232:235], v[220:223], v[58:61]
	v_mfma_f32_16x16x32_bf16 v[62:65], v[236:239], v[220:223], v[62:65]
	s_waitcnt vmcnt(8)
	s_barrier
; #define BLOAD(A_, B_, kt) do { _Pragma("unroll") for (int i = 0; i < 4; ++i) { \
;     A_[i] = *(const u32x4*)((const char*)Ap + (aoff + (unsigned)(32 * i * lda + (kt) * 64) * 2u)); B_[i] = *(const u32x4*)((const char*)Wt + (woff + (unsigned)(32 * i * K + (kt) * 64) * 2u)); } } while (0)
; #define BLOAD(A_, B_, kt) do { _Pragma("unroll") for (int i = 0; i < 4; ++i) { \
;     A_[i] = *(const u32x4*)((const char*)Ap + (aoff + (unsigned)(32 * i * lda + (kt) * 64) * 2u)); B_[i] = *(const u32x4*)((const char*)Wt + (woff + (unsigned)(32 * i * K + (kt) * 64) * 2u)); } } while (0)
; #define BSTORE(A_, B_, buf) do { _Pragma("unroll") for (int i = 0; i < 4; ++i) { \
;     *(u32x4*)&As[(buf) * GBUF + (srow + 32 * i) * LDT + sc8] = A_[i]; \
;     *(u32x4*)&Bs[(buf) * GBUF + (srow + 32 * i) * LDT + sc8] = B_[i]; } } while (0)
; template <bool ROWNORM, int NK>
; DI void gemm_main_bf(const u16* __restrict__ Ap, int lda, const u16* __restrict__ Wt, f32x16 (&acc)[2][2], char* smem, float* rinv_s) {
;     ...
;   __builtin_amdgcn_s_setprio(0);
;   BLOAD(a0, b0, 0); BLOAD(a1, b1, 1);
;   __syncthreads();
;   BSTORE(a0, b0, 0);
;   BLOAD(a0, b0, 2);
;   __syncthreads();
; #pragma unroll
;   for (int kt = 0; kt < nk; kt += 2) {
;     BCOMP(0);
;     BSTORE(a1, b1, 1);
;     if (kt + 3 < nk) BLOAD(a1, b1, kt + 3);
;     __syncthreads();
;     BCOMP(1);
;     if (kt + 2 < nk) { BSTORE(a0, b0, 0); if (kt + 4 < nk) BLOAD(a0, b0, kt + 4); }
;     __syncthreads();
;   }
	ds_read_b128 v[208:211], v240 offset:32768
	ds_read_b128 v[224:227], v241 offset:32768
	ds_read_b128 v[228:231], v241 offset:33792
	ds_read_b128 v[232:235], v241 offset:34816
	ds_read_b128 v[236:239], v241 offset:35840
	s_add_u32 m0, s52, 0x4000
	s_add_u32 s28, s28, 0x100000
	s_addc_u32 s29, s29, 0
	global_load_lds_dwordx4 v251, s[28:29]
	global_load_lds_dwordx4 v251, s[28:29] offset:1024
	s_add_u32 m0, s53, 0x4000
	s_add_u32 s30, s30, 0x30000
	s_addc_u32 s31, s31, 0
	global_load_lds_dwordx4 v251, s[30:31]
	global_load_lds_dwordx4 v251, s[30:31] offset:1024
	ds_read_b128 v[212:215], v240 offset:33792
	ds_read_b128 v[216:219], v240 offset:34816
	ds_read_b128 v[220:223], v240 offset:35840
	s_waitcnt lgkmcnt(6)
	v_mfma_f32_16x16x32_bf16 v[2:5], v[224:227], v[208:211], v[2:5]
	s_waitcnt lgkmcnt(5)
	v_mfma_f32_16x16x32_bf16 v[6:9], v[228:231], v[208:211], v[6:9]
	s_waitcnt lgkmcnt(4)
	v_mfma_f32_16x16x32_bf16 v[10:13], v[232:235], v[208:211], v[10:13]
	s_waitcnt lgkmcnt(3)
	v_mfma_f32_16x16x32_bf16 v[14:17], v[236:239], v[208:211], v[14:17]
	s_waitcnt lgkmcnt(2)
	v_mfma_f32_16x16x32_bf16 v[18:21], v[224:227], v[212:215], v[18:21]
	v_mfma_f32_16x16x32_bf16 v[22:25], v[228:231], v[212:215], v[22:25]
	v_mfma_f32_16x16x32_bf16 v[26:29], v[232:235], v[212:215], v[26:29]
	v_mfma_f32_16x16x32_bf16 v[30:33], v[236:239], v[212:215], v[30:33]
	s_waitcnt lgkmcnt(1)
	v_mfma_f32_16x16x32_bf16 v[34:37], v[224:227], v[216:219], v[34:37]
	v_mfma_f32_16x16x32_bf16 v[38:41], v[228:231], v[216:219], v[38:41]
	v_mfma_f32_16x16x32_bf16 v[42:45], v[232:235], v[216:219], v[42:45]
	v_mfma_f32_16x16x32_bf16 v[46:49], v[236:239], v[216:219], v[46:49]
	s_waitcnt lgkmcnt(0)
	v_mfma_f32_16x16x32_bf16 v[50:53], v[224:227], v[220:223], v[50:53]
	v_mfma_f32_16x16x32_bf16 v[54:57], v[228:231], v[220:223], v[54:57]
	v_mfma_f32_16x16x32_bf16 v[58:61], v[232:235], v[220:223], v[58:61]
	v_mfma_f32_16x16x32_bf16 v[62:65], v[236:239], v[220:223], v[62:65]
	s_waitcnt vmcnt(8)
	s_barrier
	ds_read_b128 v[208:211], v240 offset:49152
	ds_read_b128 v[224:227], v241 offset:49152
	ds_read_b128 v[228:231], v241 offset:50176
	ds_read_b128 v[232:235], v241 offset:51200
	ds_read_b128 v[236:239], v241 offset:52224
	s_add_u32 m0, s52, 0x8000
	s_add_u32 s28, s28, 0x100000
	s_addc_u32 s29, s29, 0
	global_load_lds_dwordx4 v251, s[28:29]
	global_load_lds_dwordx4 v251, s[28:29] offset:1024
	s_add_u32 m0, s53, 0x8000
	s_add_u32 s30, s30, 0x30000
	s_addc_u32 s31, s31, 0
	global_load_lds_dwordx4 v251, s[30:31]
	global_load_lds_dwordx4 v251, s[30:31] offset:1024
	ds_read_b128 v[212:215], v240 offset:50176
	ds_read_b128 v[216:219], v240 offset:51200
	ds_read_b128 v[220:223], v240 offset:52224
	s_waitcnt lgkmcnt(6)
	v_mfma_f32_16x16x32_bf16 v[2:5], v[224:227], v[208:211], v[2:5]
	s_waitcnt lgkmcnt(5)
	v_mfma_f32_16x16x32_bf16 v[6:9], v[228:231], v[208:211], v[6:9]
	s_waitcnt lgkmcnt(4)
	v_mfma_f32_16x16x32_bf16 v[10:13], v[232:235], v[208:211], v[10:13]
	s_waitcnt lgkmcnt(3)
	v_mfma_f32_16x16x32_bf16 v[14:17], v[236:239], v[208:211], v[14:17]
	s_waitcnt lgkmcnt(2)
	v_mfma_f32_16x16x32_bf16 v[18:21], v[224:227], v[212:215], v[18:21]
	v_mfma_f32_16x16x32_bf16 v[22:25], v[228:231], v[212:215], v[22:25]
	v_mfma_f32_16x16x32_bf16 v[26:29], v[232:235], v[212:215], v[26:29]
	v_mfma_f32_16x16x32_bf16 v[30:33], v[236:239], v[212:215], v[30:33]
	s_waitcnt lgkmcnt(1)
	v_mfma_f32_16x16x32_bf16 v[34:37], v[224:227], v[216:219], v[34:37]
	v_mfma_f32_16x16x32_bf16 v[38:41], v[228:231], v[216:219], v[38:41]
	v_mfma_f32_16x16x32_bf16 v[42:45], v[232:235], v[216:219], v[42:45]
	v_mfma_f32_16x16x32_bf16 v[46:49], v[236:239], v[216:219], v[46:49]
	s_waitcnt lgkmcnt(0)
	v_mfma_f32_16x16x32_bf16 v[50:53], v[224:227], v[220:223], v[50:53]
	v_mfma_f32_16x16x32_bf16 v[54:57], v[228:231], v[220:223], v[54:57]
	v_mfma_f32_16x16x32_bf16 v[58:61], v[232:235], v[220:223], v[58:61]
	v_mfma_f32_16x16x32_bf16 v[62:65], v[236:239], v[220:223], v[62:65]
	s_sub_u32 s74, s74, 1
	s_cmp_lg_u32 s74, 0
	s_cbranch_scc1 .Lbr_gate_k
	s_waitcnt vmcnt(8)
	s_barrier
	ds_read_b128 v[208:211], v240 offset:0
	ds_read_b128 v[224:227], v241 offset:0
	ds_read_b128 v[228:231], v241 offset:1024
	ds_read_b128 v[232:235], v241 offset:2048
	ds_read_b128 v[236:239], v241 offset:3072
	s_add_u32 m0, s52, 0xc000
	s_add_u32 s28, s28, 0x100000
	s_addc_u32 s29, s29, 0
	global_load_lds_dwordx4 v251, s[28:29]
	global_load_lds_dwordx4 v251, s[28:29] offset:1024
	s_add_u32 m0, s53, 0xc000
	s_add_u32 s30, s30, 0x30000
	s_addc_u32 s31, s31, 0
	global_load_lds_dwordx4 v251, s[30:31]
	global_load_lds_dwordx4 v251, s[30:31] offset:1024
	ds_read_b128 v[212:215], v240 offset:1024
	ds_read_b128 v[216:219], v240 offset:2048
	ds_read_b128 v[220:223], v240 offset:3072
	s_waitcnt lgkmcnt(6)
	v_mfma_f32_16x16x32_bf16 v[2:5], v[224:227], v[208:211], v[2:5]
	s_waitcnt lgkmcnt(5)
	v_mfma_f32_16x16x32_bf16 v[6:9], v[228:231], v[208:211], v[6:9]
	s_waitcnt lgkmcnt(4)
	v_mfma_f32_16x16x32_bf16 v[10:13], v[232:235], v[208:211], v[10:13]
	s_waitcnt lgkmcnt(3)
	v_mfma_f32_16x16x32_bf16 v[14:17], v[236:239], v[208:211], v[14:17]
	s_waitcnt lgkmcnt(2)
	v_mfma_f32_16x16x32_bf16 v[18:21], v[224:227], v[212:215], v[18:21]
	v_mfma_f32_16x16x32_bf16 v[22:25], v[228:231], v[212:215], v[22:25]
	v_mfma_f32_16x16x32_bf16 v[26:29], v[232:235], v[212:215], v[26:29]
	v_mfma_f32_16x16x32_bf16 v[30:33], v[236:239], v[212:215], v[30:33]
	s_waitcnt lgkmcnt(1)
	v_mfma_f32_16x16x32_bf16 v[34:37], v[224:227], v[216:219], v[34:37]
	v_mfma_f32_16x16x32_bf16 v[38:41], v[228:231], v[216:219], v[38:41]
	v_mfma_f32_16x16x32_bf16 v[42:45], v[232:235], v[216:219], v[42:45]
	v_mfma_f32_16x16x32_bf16 v[46:49], v[236:239], v[216:219], v[46:49]
	s_waitcnt lgkmcnt(0)
	v_mfma_f32_16x16x32_bf16 v[50:53], v[224:227], v[220:223], v[50:53]
	v_mfma_f32_16x16x32_bf16 v[54:57], v[228:231], v[220:223], v[54:57]
	v_mfma_f32_16x16x32_bf16 v[58:61], v[232:235], v[220:223], v[58:61]
	v_mfma_f32_16x16x32_bf16 v[62:65], v[236:239], v[220:223], v[62:65]
	s_waitcnt vmcnt(8)
	s_barrier
; #define BLOAD(A_, B_, kt) do { _Pragma("unroll") for (int i = 0; i < 4; ++i) { \
;     A_[i] = *(const u32x4*)((const char*)Ap + (aoff + (unsigned)(32 * i * lda + (kt) * 64) * 2u)); B_[i] = *(const u32x4*)((const char*)Wt + (woff + (unsigned)(32 * i * K + (kt) * 64) * 2u)); } } while (0)
; #define BLOAD(A_, B_, kt) do { _Pragma("unroll") for (int i = 0; i < 4; ++i) { \
;     A_[i] = *(const u32x4*)((const char*)Ap + (aoff + (unsigned)(32 * i * lda + (kt) * 64) * 2u)); B_[i] = *(const u32x4*)((const char*)Wt + (woff + (unsigned)(32 * i * K + (kt) * 64) * 2u)); } } while (0)
; #define BSTORE(A_, B_, buf) do { _Pragma("unroll") for (int i = 0; i < 4; ++i) { \
;     *(u32x4*)&As[(buf) * GBUF + (srow + 32 * i) * LDT + sc8] = A_[i]; \
;     *(u32x4*)&Bs[(buf) * GBUF + (srow + 32 * i) * LDT + sc8] = B_[i]; } } while (0)
; template <bool ROWNORM, int NK>
; DI void gemm_main_bf(const u16* __restrict__ Ap, int lda, const u16* __restrict__ Wt, f32x16 (&acc)[2][2], char* smem, float* rinv_s) {
;     ...
;   __builtin_amdgcn_s_setprio(0);
;   BLOAD(a0, b0, 0); BLOAD(a1, b1, 1);
;   __syncthreads();
;   BSTORE(a0, b0, 0);
;   BLOAD(a0, b0, 2);
;   __syncthreads();
; #pragma unroll
;   for (int kt = 0; kt < nk; kt += 2) {
;     BCOMP(0);
;     BSTORE(a1, b1, 1);
;     if (kt + 3 < nk) BLOAD(a1, b1, kt + 3);
;     __syncthreads();
;     BCOMP(1);
;     if (kt + 2 < nk) { BSTORE(a0, b0, 0); if (kt + 4 < nk) BLOAD(a0, b0, kt + 4); }
;     __syncthreads();
;   }
; DI void tile_branch(const Params& p, int l, int tile, char* smem) {
;     ...
; #pragma unroll
;       for (int mt = 0; mt < 2; ++mt)
; #pragma unroll
;         for (int g4 = 0; g4 < 4; ++g4) {
;           const f32x4 r4 = *(const f32x4*)&rinv_s[wm * 64 + mt * 32 + 8 * g4 + 4 * hi];
	ds_read_b128 v[208:211], v240 offset:16384
	ds_read_b128 v[224:227], v241 offset:16384
	ds_read_b128 v[228:231], v241 offset:17408
	ds_read_b128 v[232:235], v241 offset:18432
	ds_read_b128 v[236:239], v241 offset:19456
	ds_read_b128 v[212:215], v240 offset:17408
	ds_read_b128 v[216:219], v240 offset:18432
	ds_read_b128 v[220:223], v240 offset:19456
	s_waitcnt lgkmcnt(6)
	v_mfma_f32_16x16x32_bf16 v[2:5], v[224:227], v[208:211], v[2:5]
	s_waitcnt lgkmcnt(5)
	v_mfma_f32_16x16x32_bf16 v[6:9], v[228:231], v[208:211], v[6:9]
	s_waitcnt lgkmcnt(4)
	v_mfma_f32_16x16x32_bf16 v[10:13], v[232:235], v[208:211], v[10:13]
	s_waitcnt lgkmcnt(3)
	v_mfma_f32_16x16x32_bf16 v[14:17], v[236:239], v[208:211], v[14:17]
	s_waitcnt lgkmcnt(2)
	v_mfma_f32_16x16x32_bf16 v[18:21], v[224:227], v[212:215], v[18:21]
	v_mfma_f32_16x16x32_bf16 v[22:25], v[228:231], v[212:215], v[22:25]
	v_mfma_f32_16x16x32_bf16 v[26:29], v[232:235], v[212:215], v[26:29]
	v_mfma_f32_16x16x32_bf16 v[30:33], v[236:239], v[212:215], v[30:33]
	s_waitcnt lgkmcnt(1)
	v_mfma_f32_16x16x32_bf16 v[34:37], v[224:227], v[216:219], v[34:37]
	v_mfma_f32_16x16x32_bf16 v[38:41], v[228:231], v[216:219], v[38:41]
	v_mfma_f32_16x16x32_bf16 v[42:45], v[232:235], v[216:219], v[42:45]
	v_mfma_f32_16x16x32_bf16 v[46:49], v[236:239], v[216:219], v[46:49]
	s_waitcnt lgkmcnt(0)
	v_mfma_f32_16x16x32_bf16 v[50:53], v[224:227], v[220:223], v[50:53]
	v_mfma_f32_16x16x32_bf16 v[54:57], v[228:231], v[220:223], v[54:57]
	v_mfma_f32_16x16x32_bf16 v[58:61], v[232:235], v[220:223], v[58:61]
	v_mfma_f32_16x16x32_bf16 v[62:65], v[236:239], v[220:223], v[62:65]
	s_waitcnt vmcnt(4)
	s_barrier
	ds_read_b128 v[208:211], v240 offset:32768
	ds_read_b128 v[224:227], v241 offset:32768
	ds_read_b128 v[228:231], v241 offset:33792
	ds_read_b128 v[232:235], v241 offset:34816
	ds_read_b128 v[236:239], v241 offset:35840
	ds_read_b128 v[212:215], v240 offset:33792
	ds_read_b128 v[216:219], v240 offset:34816
	ds_read_b128 v[220:223], v240 offset:35840
	s_waitcnt lgkmcnt(6)
	v_mfma_f32_16x16x32_bf16 v[2:5], v[224:227], v[208:211], v[2:5]
	s_waitcnt lgkmcnt(5)
	v_mfma_f32_16x16x32_bf16 v[6:9], v[228:231], v[208:211], v[6:9]
	s_waitcnt lgkmcnt(4)
	v_mfma_f32_16x16x32_bf16 v[10:13], v[232:235], v[208:211], v[10:13]
	s_waitcnt lgkmcnt(3)
	v_mfma_f32_16x16x32_bf16 v[14:17], v[236:239], v[208:211], v[14:17]
	s_waitcnt lgkmcnt(2)
	v_mfma_f32_16x16x32_bf16 v[18:21], v[224:227], v[212:215], v[18:21]
	v_mfma_f32_16x16x32_bf16 v[22:25], v[228:231], v[212:215], v[22:25]
	v_mfma_f32_16x16x32_bf16 v[26:29], v[232:235], v[212:215], v[26:29]
	v_mfma_f32_16x16x32_bf16 v[30:33], v[236:239], v[212:215], v[30:33]
	s_waitcnt lgkmcnt(1)
	v_mfma_f32_16x16x32_bf16 v[34:37], v[224:227], v[216:219], v[34:37]
	v_mfma_f32_16x16x32_bf16 v[38:41], v[228:231], v[216:219], v[38:41]
	v_mfma_f32_16x16x32_bf16 v[42:45], v[232:235], v[216:219], v[42:45]
	v_mfma_f32_16x16x32_bf16 v[46:49], v[236:239], v[216:219], v[46:49]
	s_waitcnt lgkmcnt(0)
	v_mfma_f32_16x16x32_bf16 v[50:53], v[224:227], v[220:223], v[50:53]
	v_mfma_f32_16x16x32_bf16 v[54:57], v[228:231], v[220:223], v[54:57]
	v_mfma_f32_16x16x32_bf16 v[58:61], v[232:235], v[220:223], v[58:61]
	v_mfma_f32_16x16x32_bf16 v[62:65], v[236:239], v[220:223], v[62:65]
	s_waitcnt vmcnt(0)
	s_barrier
	ds_read_b128 v[208:211], v240 offset:49152
	ds_read_b128 v[224:227], v241 offset:49152
	ds_read_b128 v[228:231], v241 offset:50176
	ds_read_b128 v[232:235], v241 offset:51200
	ds_read_b128 v[236:239], v241 offset:52224
	ds_read_b128 v[212:215], v240 offset:50176
	ds_read_b128 v[216:219], v240 offset:51200
	ds_read_b128 v[220:223], v240 offset:52224
	s_waitcnt lgkmcnt(6)
	v_mfma_f32_16x16x32_bf16 v[2:5], v[224:227], v[208:211], v[2:5]
	s_waitcnt lgkmcnt(5)
	v_mfma_f32_16x16x32_bf16 v[6:9], v[228:231], v[208:211], v[6:9]
	s_waitcnt lgkmcnt(4)
	v_mfma_f32_16x16x32_bf16 v[10:13], v[232:235], v[208:211], v[10:13]
	s_waitcnt lgkmcnt(3)
	v_mfma_f32_16x16x32_bf16 v[14:17], v[236:239], v[208:211], v[14:17]
	s_waitcnt lgkmcnt(2)
	v_mfma_f32_16x16x32_bf16 v[18:21], v[224:227], v[212:215], v[18:21]
	v_mfma_f32_16x16x32_bf16 v[22:25], v[228:231], v[212:215], v[22:25]
	v_mfma_f32_16x16x32_bf16 v[26:29], v[232:235], v[212:215], v[26:29]
	v_mfma_f32_16x16x32_bf16 v[30:33], v[236:239], v[212:215], v[30:33]
	s_waitcnt lgkmcnt(1)
	v_mfma_f32_16x16x32_bf16 v[34:37], v[224:227], v[216:219], v[34:37]
	v_mfma_f32_16x16x32_bf16 v[38:41], v[228:231], v[216:219], v[38:41]
	v_mfma_f32_16x16x32_bf16 v[42:45], v[232:235], v[216:219], v[42:45]
	v_mfma_f32_16x16x32_bf16 v[46:49], v[236:239], v[216:219], v[46:49]
	s_waitcnt lgkmcnt(0)
	v_mfma_f32_16x16x32_bf16 v[50:53], v[224:227], v[220:223], v[50:53]
	v_mfma_f32_16x16x32_bf16 v[54:57], v[228:231], v[220:223], v[54:57]
	v_mfma_f32_16x16x32_bf16 v[58:61], v[232:235], v[220:223], v[58:61]
	v_mfma_f32_16x16x32_bf16 v[62:65], v[236:239], v[220:223], v[62:65]
	s_mov_b64 s[28:29], s[48:49]
	s_mov_b64 s[30:31], s[50:51]
	ds_read_b32 v162, v250 offset:0
	ds_read_b32 v163, v250 offset:64
	ds_read_b32 v164, v250 offset:128
	ds_read_b32 v165, v250 offset:192
	s_waitcnt lgkmcnt(0)
; DI unsigned pk2(float a, float b) { f2_t v = {a, b}; bf2_t r = __builtin_convertvector(v, bf2_t); return __builtin_bit_cast(unsigned, r); }
; DI void tile_branch(const Params& p, int l, int tile, char* smem) {
;     ...
; #pragma unroll
;       for (int mt = 0; mt < 2; ++mt)
; #pragma unroll
;         for (int g4 = 0; g4 < 4; ++g4) {
;           const f32x4 r4 = *(const f32x4*)&rinv_s[wm * 64 + mt * 32 + 8 * g4 + 4 * hi];
; #pragma unroll
;           for (int nt = 0; nt < 2; ++nt) {
;             const float s0 = 1.f / (1.f + __expf(-accg[mt][nt][4 * g4 + 0] * r4[0])), s1 = 1.f / (1.f + __expf(-accg[mt][nt][4 * g4 + 1] * r4[1]));
;             const float s2 = 1.f / (1.f + __expf(-accg[mt][nt][4 * g4 + 2] * r4[2])), s3 = 1.f / (1.f + __expf(-accg[mt][nt][4 * g4 + 3] * r4[3]));
;             gpk[mt][nt][2 * g4] = pk2(s0, s1); gpk[mt][nt][2 * g4 + 1] = pk2(s2, s3);
;           }
;         }
	v_mul_f32_e32 v162, 0xbfb8aa3b, v162
	v_mul_f32_e32 v163, 0xbfb8aa3b, v163
	v_mul_f32_e32 v164, 0xbfb8aa3b, v164
	v_mul_f32_e32 v165, 0xbfb8aa3b, v165
	v_mul_f32_e32 v166, v162, v2
	v_mul_f32_e32 v167, v162, v3
	v_mul_f32_e32 v168, v162, v4
	v_mul_f32_e32 v169, v162, v5
	v_exp_f32_e32 v166, v166
	v_exp_f32_e32 v167, v167
	v_exp_f32_e32 v168, v168
	v_exp_f32_e32 v169, v169
	v_add_f32_e32 v166, 1.0, v166
	v_add_f32_e32 v167, 1.0, v167
	v_add_f32_e32 v168, 1.0, v168
	v_add_f32_e32 v169, 1.0, v169
	v_rcp_f32_e32 v166, v166
	v_rcp_f32_e32 v167, v167
	v_rcp_f32_e32 v168, v168
	v_rcp_f32_e32 v169, v169
	v_cvt_pk_bf16_f32 v130, v166, v167
	v_cvt_pk_bf16_f32 v131, v168, v169
	v_mul_f32_e32 v166, v162, v6
	v_mul_f32_e32 v167, v162, v7
	v_mul_f32_e32 v168, v162, v8
	v_mul_f32_e32 v169, v162, v9
	v_exp_f32_e32 v166, v166
	v_exp_f32_e32 v167, v167
	v_exp_f32_e32 v168, v168
	v_exp_f32_e32 v169, v169
	v_add_f32_e32 v166, 1.0, v166
	v_add_f32_e32 v167, 1.0, v167
	v_add_f32_e32 v168, 1.0, v168
	v_add_f32_e32 v169, 1.0, v169
	v_rcp_f32_e32 v166, v166
	v_rcp_f32_e32 v167, v167
	v_rcp_f32_e32 v168, v168
	v_rcp_f32_e32 v169, v169
	v_cvt_pk_bf16_f32 v132, v166, v167
	v_cvt_pk_bf16_f32 v133, v168, v169
	v_mul_f32_e32 v166, v162, v10
	v_mul_f32_e32 v167, v162, v11
	v_mul_f32_e32 v168, v162, v12
	v_mul_f32_e32 v169, v162, v13
	v_exp_f32_e32 v166, v166
	v_exp_f32_e32 v167, v167
	v_exp_f32_e32 v168, v168
	v_exp_f32_e32 v169, v169
	v_add_f32_e32 v166, 1.0, v166
	v_add_f32_e32 v167, 1.0, v167
	v_add_f32_e32 v168, 1.0, v168
	v_add_f32_e32 v169, 1.0, v169
	v_rcp_f32_e32 v166, v166
	v_rcp_f32_e32 v167, v167
	v_rcp_f32_e32 v168, v168
	v_rcp_f32_e32 v169, v169
	v_cvt_pk_bf16_f32 v134, v166, v167
	v_cvt_pk_bf16_f32 v135, v168, v169
	v_mul_f32_e32 v166, v162, v14
	v_mul_f32_e32 v167, v162, v15
	v_mul_f32_e32 v168, v162, v16
	v_mul_f32_e32 v169, v162, v17
	v_exp_f32_e32 v166, v166
	v_exp_f32_e32 v167, v167
	v_exp_f32_e32 v168, v168
	v_exp_f32_e32 v169, v169
	v_add_f32_e32 v166, 1.0, v166
	v_add_f32_e32 v167, 1.0, v167
	v_add_f32_e32 v168, 1.0, v168
	v_add_f32_e32 v169, 1.0, v169
	v_rcp_f32_e32 v166, v166
	v_rcp_f32_e32 v167, v167
	v_rcp_f32_e32 v168, v168
	v_rcp_f32_e32 v169, v169
	v_cvt_pk_bf16_f32 v136, v166, v167
	v_cvt_pk_bf16_f32 v137, v168, v169
	v_mul_f32_e32 v166, v163, v18
	v_mul_f32_e32 v167, v163, v19
	v_mul_f32_e32 v168, v163, v20
	v_mul_f32_e32 v169, v163, v21
	v_exp_f32_e32 v166, v166
	v_exp_f32_e32 v167, v167
	v_exp_f32_e32 v168, v168
	v_exp_f32_e32 v169, v169
	v_add_f32_e32 v166, 1.0, v166
	v_add_f32_e32 v167, 1.0, v167
	v_add_f32_e32 v168, 1.0, v168
	v_add_f32_e32 v169, 1.0, v169
	v_rcp_f32_e32 v166, v166
	v_rcp_f32_e32 v167, v167
	v_rcp_f32_e32 v168, v168
	v_rcp_f32_e32 v169, v169
	v_cvt_pk_bf16_f32 v138, v166, v167
	v_cvt_pk_bf16_f32 v139, v168, v169
	v_mul_f32_e32 v166, v163, v22
	v_mul_f32_e32 v167, v163, v23
	v_mul_f32_e32 v168, v163, v24
	v_mul_f32_e32 v169, v163, v25
	v_exp_f32_e32 v166, v166
	v_exp_f32_e32 v167, v167
	v_exp_f32_e32 v168, v168
	v_exp_f32_e32 v169, v169
	v_add_f32_e32 v166, 1.0, v166
	v_add_f32_e32 v167, 1.0, v167
	v_add_f32_e32 v168, 1.0, v168
	v_add_f32_e32 v169, 1.0, v169
	v_rcp_f32_e32 v166, v166
	v_rcp_f32_e32 v167, v167
	v_rcp_f32_e32 v168, v168
	v_rcp_f32_e32 v169, v169
	v_cvt_pk_bf16_f32 v140, v166, v167
	v_cvt_pk_bf16_f32 v141, v168, v169
	v_mul_f32_e32 v166, v163, v26
	v_mul_f32_e32 v167, v163, v27
	v_mul_f32_e32 v168, v163, v28
	v_mul_f32_e32 v169, v163, v29
	v_exp_f32_e32 v166, v166
	v_exp_f32_e32 v167, v167
	v_exp_f32_e32 v168, v168
	v_exp_f32_e32 v169, v169
	v_add_f32_e32 v166, 1.0, v166
	v_add_f32_e32 v167, 1.0, v167
	v_add_f32_e32 v168, 1.0, v168
	v_add_f32_e32 v169, 1.0, v169
	v_rcp_f32_e32 v166, v166
	v_rcp_f32_e32 v167, v167
	v_rcp_f32_e32 v168, v168
	v_rcp_f32_e32 v169, v169
	v_cvt_pk_bf16_f32 v142, v166, v167
	v_cvt_pk_bf16_f32 v143, v168, v169
	v_mul_f32_e32 v166, v163, v30
	v_mul_f32_e32 v167, v163, v31
	v_mul_f32_e32 v168, v163, v32
	v_mul_f32_e32 v169, v163, v33
	v_exp_f32_e32 v166, v166
	v_exp_f32_e32 v167, v167
	v_exp_f32_e32 v168, v168
	v_exp_f32_e32 v169, v169
	v_add_f32_e32 v166, 1.0, v166
	v_add_f32_e32 v167, 1.0, v167
	v_add_f32_e32 v168, 1.0, v168
	v_add_f32_e32 v169, 1.0, v169
	v_rcp_f32_e32 v166, v166
	v_rcp_f32_e32 v167, v167
	v_rcp_f32_e32 v168, v168
	v_rcp_f32_e32 v169, v169
	v_cvt_pk_bf16_f32 v144, v166, v167
	v_cvt_pk_bf16_f32 v145, v168, v169
	v_mul_f32_e32 v166, v164, v34
	v_mul_f32_e32 v167, v164, v35
	v_mul_f32_e32 v168, v164, v36
	v_mul_f32_e32 v169, v164, v37
	v_exp_f32_e32 v166, v166
	v_exp_f32_e32 v167, v167
	v_exp_f32_e32 v168, v168
	v_exp_f32_e32 v169, v169
	v_add_f32_e32 v166, 1.0, v166
	v_add_f32_e32 v167, 1.0, v167
	v_add_f32_e32 v168, 1.0, v168
	v_add_f32_e32 v169, 1.0, v169
	v_rcp_f32_e32 v166, v166
	v_rcp_f32_e32 v167, v167
	v_rcp_f32_e32 v168, v168
	v_rcp_f32_e32 v169, v169
	v_cvt_pk_bf16_f32 v146, v166, v167
	v_cvt_pk_bf16_f32 v147, v168, v169
	v_mul_f32_e32 v166, v164, v38
	v_mul_f32_e32 v167, v164, v39
	v_mul_f32_e32 v168, v164, v40
	v_mul_f32_e32 v169, v164, v41
	v_exp_f32_e32 v166, v166
	v_exp_f32_e32 v167, v167
	v_exp_f32_e32 v168, v168
	v_exp_f32_e32 v169, v169
	v_add_f32_e32 v166, 1.0, v166
	v_add_f32_e32 v167, 1.0, v167
	v_add_f32_e32 v168, 1.0, v168
	v_add_f32_e32 v169, 1.0, v169
	v_rcp_f32_e32 v166, v166
	v_rcp_f32_e32 v167, v167
	v_rcp_f32_e32 v168, v168
	v_rcp_f32_e32 v169, v169
	v_cvt_pk_bf16_f32 v148, v166, v167
	v_cvt_pk_bf16_f32 v149, v168, v169
	v_mul_f32_e32 v166, v164, v42
	v_mul_f32_e32 v167, v164, v43
	v_mul_f32_e32 v168, v164, v44
	v_mul_f32_e32 v169, v164, v45
	v_exp_f32_e32 v166, v166
	v_exp_f32_e32 v167, v167
	v_exp_f32_e32 v168, v168
	v_exp_f32_e32 v169, v169
; DI unsigned pk2(float a, float b) { f2_t v = {a, b}; bf2_t r = __builtin_convertvector(v, bf2_t); return __builtin_bit_cast(unsigned, r); }
; DI void tile_branch(const Params& p, int l, int tile, char* smem) {
;     ...
; #pragma unroll
;       for (int mt = 0; mt < 2; ++mt)
; #pragma unroll
;         for (int g4 = 0; g4 < 4; ++g4) {
;           const f32x4 r4 = *(const f32x4*)&rinv_s[wm * 64 + mt * 32 + 8 * g4 + 4 * hi];
; #pragma unroll
;           for (int nt = 0; nt < 2; ++nt) {
;             const float s0 = 1.f / (1.f + __expf(-accg[mt][nt][4 * g4 + 0] * r4[0])), s1 = 1.f / (1.f + __expf(-accg[mt][nt][4 * g4 + 1] * r4[1]));
;             const float s2 = 1.f / (1.f + __expf(-accg[mt][nt][4 * g4 + 2] * r4[2])), s3 = 1.f / (1.f + __expf(-accg[mt][nt][4 * g4 + 3] * r4[3]));
;             gpk[mt][nt][2 * g4] = pk2(s0, s1); gpk[mt][nt][2 * g4 + 1] = pk2(s2, s3);
;           }
;         }
;     }
;     f32x16 acc[2][2]; zero_acc(acc);
;     gemm_main_bf<false, 8>((const u16*)(p.ws + OFF_BR) + (size_t)(br * CT + m0) * 512, 512,
;                             (const u16*)(p.ws + OFF_WBR + (l * 3 + br) * SZ_WBR) + (size_t)n0 * 512, acc, smem, nullptr);
	v_add_f32_e32 v166, 1.0, v166
	v_add_f32_e32 v167, 1.0, v167
	v_add_f32_e32 v168, 1.0, v168
	v_add_f32_e32 v169, 1.0, v169
	v_rcp_f32_e32 v166, v166
	v_rcp_f32_e32 v167, v167
	v_rcp_f32_e32 v168, v168
	v_rcp_f32_e32 v169, v169
	v_cvt_pk_bf16_f32 v150, v166, v167
	v_cvt_pk_bf16_f32 v151, v168, v169
	v_mul_f32_e32 v166, v164, v46
	v_mul_f32_e32 v167, v164, v47
	v_mul_f32_e32 v168, v164, v48
	v_mul_f32_e32 v169, v164, v49
	v_exp_f32_e32 v166, v166
	v_exp_f32_e32 v167, v167
	v_exp_f32_e32 v168, v168
	v_exp_f32_e32 v169, v169
	v_add_f32_e32 v166, 1.0, v166
	v_add_f32_e32 v167, 1.0, v167
	v_add_f32_e32 v168, 1.0, v168
	v_add_f32_e32 v169, 1.0, v169
	v_rcp_f32_e32 v166, v166
	v_rcp_f32_e32 v167, v167
	v_rcp_f32_e32 v168, v168
	v_rcp_f32_e32 v169, v169
	v_cvt_pk_bf16_f32 v152, v166, v167
	v_cvt_pk_bf16_f32 v153, v168, v169
	v_mul_f32_e32 v166, v165, v50
	v_mul_f32_e32 v167, v165, v51
	v_mul_f32_e32 v168, v165, v52
	v_mul_f32_e32 v169, v165, v53
	v_exp_f32_e32 v166, v166
	v_exp_f32_e32 v167, v167
	v_exp_f32_e32 v168, v168
	v_exp_f32_e32 v169, v169
	v_add_f32_e32 v166, 1.0, v166
	v_add_f32_e32 v167, 1.0, v167
	v_add_f32_e32 v168, 1.0, v168
	v_add_f32_e32 v169, 1.0, v169
	v_rcp_f32_e32 v166, v166
	v_rcp_f32_e32 v167, v167
	v_rcp_f32_e32 v168, v168
	v_rcp_f32_e32 v169, v169
	v_cvt_pk_bf16_f32 v154, v166, v167
	v_cvt_pk_bf16_f32 v155, v168, v169
	v_mul_f32_e32 v166, v165, v54
	v_mul_f32_e32 v167, v165, v55
	v_mul_f32_e32 v168, v165, v56
	v_mul_f32_e32 v169, v165, v57
	v_exp_f32_e32 v166, v166
	v_exp_f32_e32 v167, v167
	v_exp_f32_e32 v168, v168
	v_exp_f32_e32 v169, v169
	v_add_f32_e32 v166, 1.0, v166
	v_add_f32_e32 v167, 1.0, v167
	v_add_f32_e32 v168, 1.0, v168
	v_add_f32_e32 v169, 1.0, v169
	v_rcp_f32_e32 v166, v166
	v_rcp_f32_e32 v167, v167
	v_rcp_f32_e32 v168, v168
	v_rcp_f32_e32 v169, v169
	v_cvt_pk_bf16_f32 v156, v166, v167
	v_cvt_pk_bf16_f32 v157, v168, v169
	v_mul_f32_e32 v166, v165, v58
	v_mul_f32_e32 v167, v165, v59
	v_mul_f32_e32 v168, v165, v60
	v_mul_f32_e32 v169, v165, v61
	v_exp_f32_e32 v166, v166
	v_exp_f32_e32 v167, v167
	v_exp_f32_e32 v168, v168
	v_exp_f32_e32 v169, v169
	v_add_f32_e32 v166, 1.0, v166
	v_add_f32_e32 v167, 1.0, v167
	v_add_f32_e32 v168, 1.0, v168
	v_add_f32_e32 v169, 1.0, v169
	v_rcp_f32_e32 v166, v166
	v_rcp_f32_e32 v167, v167
	v_rcp_f32_e32 v168, v168
	v_rcp_f32_e32 v169, v169
	v_cvt_pk_bf16_f32 v158, v166, v167
	v_cvt_pk_bf16_f32 v159, v168, v169
	v_mul_f32_e32 v166, v165, v62
	v_mul_f32_e32 v167, v165, v63
	v_mul_f32_e32 v168, v165, v64
	v_mul_f32_e32 v169, v165, v65
	v_exp_f32_e32 v166, v166
	v_exp_f32_e32 v167, v167
	v_exp_f32_e32 v168, v168
	v_exp_f32_e32 v169, v169
	v_add_f32_e32 v166, 1.0, v166
	v_add_f32_e32 v167, 1.0, v167
	v_add_f32_e32 v168, 1.0, v168
	v_add_f32_e32 v169, 1.0, v169
	v_rcp_f32_e32 v166, v166
	v_rcp_f32_e32 v167, v167
	v_rcp_f32_e32 v168, v168
	v_rcp_f32_e32 v169, v169
	v_cvt_pk_bf16_f32 v160, v166, v167
	v_cvt_pk_bf16_f32 v161, v168, v169
	s_add_u32 m0, s52, 0x0
	s_nop 0
	global_load_lds_dwordx4 v244, s[28:29]
	global_load_lds_dwordx4 v245, s[28:29] offset:1024
	s_add_u32 m0, s53, 0x0
	s_nop 0
	global_load_lds_dwordx4 v251, s[30:31]
	global_load_lds_dwordx4 v251, s[30:31] offset:1024
	s_add_u32 m0, s52, 0x4000
	s_add_u32 s28, s28, 0x40
	s_addc_u32 s29, s29, 0
	global_load_lds_dwordx4 v244, s[28:29]
	global_load_lds_dwordx4 v245, s[28:29] offset:1024
	s_add_u32 m0, s53, 0x4000
	s_add_u32 s30, s30, 0x10000
	s_addc_u32 s31, s31, 0
	global_load_lds_dwordx4 v251, s[30:31]
	global_load_lds_dwordx4 v251, s[30:31] offset:1024
	s_add_u32 m0, s52, 0x8000
	s_add_u32 s28, s28, 0x40
	s_addc_u32 s29, s29, 0
	global_load_lds_dwordx4 v244, s[28:29]
	global_load_lds_dwordx4 v245, s[28:29] offset:1024
	s_add_u32 m0, s53, 0x8000
	s_add_u32 s30, s30, 0x10000
	s_addc_u32 s31, s31, 0
	global_load_lds_dwordx4 v251, s[30:31]
	global_load_lds_dwordx4 v251, s[30:31] offset:1024
	s_waitcnt vmcnt(8)
	s_barrier
	ds_read_b128 v[208:211], v240 offset:0
	ds_read_b128 v[224:227], v241 offset:0
	ds_read_b128 v[228:231], v241 offset:1024
	ds_read_b128 v[232:235], v241 offset:2048
	ds_read_b128 v[236:239], v241 offset:3072
	s_add_u32 m0, s52, 0xc000
	s_add_u32 s28, s28, 0x40
	s_addc_u32 s29, s29, 0
	global_load_lds_dwordx4 v244, s[28:29]
	global_load_lds_dwordx4 v245, s[28:29] offset:1024
	s_add_u32 m0, s53, 0xc000
	s_add_u32 s30, s30, 0x10000
	s_addc_u32 s31, s31, 0
	global_load_lds_dwordx4 v251, s[30:31]
	global_load_lds_dwordx4 v251, s[30:31] offset:1024
	ds_read_b128 v[212:215], v240 offset:1024
	ds_read_b128 v[216:219], v240 offset:2048
	ds_read_b128 v[220:223], v240 offset:3072
	s_waitcnt lgkmcnt(6)
	v_mfma_f32_16x16x32_bf16 v[2:5], v[224:227], v[208:211], 0
	s_waitcnt lgkmcnt(5)
	v_mfma_f32_16x16x32_bf16 v[6:9], v[228:231], v[208:211], 0
	s_waitcnt lgkmcnt(4)
	v_mfma_f32_16x16x32_bf16 v[10:13], v[232:235], v[208:211], 0
	s_waitcnt lgkmcnt(3)
	v_mfma_f32_16x16x32_bf16 v[14:17], v[236:239], v[208:211], 0
	s_waitcnt lgkmcnt(2)
	v_mfma_f32_16x16x32_bf16 v[18:21], v[224:227], v[212:215], 0
	v_mfma_f32_16x16x32_bf16 v[22:25], v[228:231], v[212:215], 0
	v_mfma_f32_16x16x32_bf16 v[26:29], v[232:235], v[212:215], 0
	v_mfma_f32_16x16x32_bf16 v[30:33], v[236:239], v[212:215], 0
	s_waitcnt lgkmcnt(1)
	v_mfma_f32_16x16x32_bf16 v[34:37], v[224:227], v[216:219], 0
	v_mfma_f32_16x16x32_bf16 v[38:41], v[228:231], v[216:219], 0
	v_mfma_f32_16x16x32_bf16 v[42:45], v[232:235], v[216:219], 0
	v_mfma_f32_16x16x32_bf16 v[46:49], v[236:239], v[216:219], 0
	s_waitcnt lgkmcnt(0)
	v_mfma_f32_16x16x32_bf16 v[50:53], v[224:227], v[220:223], 0
	v_mfma_f32_16x16x32_bf16 v[54:57], v[228:231], v[220:223], 0
	v_mfma_f32_16x16x32_bf16 v[58:61], v[232:235], v[220:223], 0
	v_mfma_f32_16x16x32_bf16 v[62:65], v[236:239], v[220:223], 0
	s_waitcnt vmcnt(8)
	s_barrier
; #define BLOAD(A_, B_, kt) do { _Pragma("unroll") for (int i = 0; i < 4; ++i) { \
;     A_[i] = *(const u32x4*)((const char*)Ap + (aoff + (unsigned)(32 * i * lda + (kt) * 64) * 2u)); B_[i] = *(const u32x4*)((const char*)Wt + (woff + (unsigned)(32 * i * K + (kt) * 64) * 2u)); } } while (0)
; #define BLOAD(A_, B_, kt) do { _Pragma("unroll") for (int i = 0; i < 4; ++i) { \
;     A_[i] = *(const u32x4*)((const char*)Ap + (aoff + (unsigned)(32 * i * lda + (kt) * 64) * 2u)); B_[i] = *(const u32x4*)((const char*)Wt + (woff + (unsigned)(32 * i * K + (kt) * 64) * 2u)); } } while (0)
; #define BSTORE(A_, B_, buf) do { _Pragma("unroll") for (int i = 0; i < 4; ++i) { \
;     *(u32x4*)&As[(buf) * GBUF + (srow + 32 * i) * LDT + sc8] = A_[i]; \
;     *(u32x4*)&Bs[(buf) * GBUF + (srow + 32 * i) * LDT + sc8] = B_[i]; } } while (0)
; template <bool ROWNORM, int NK>
; DI void gemm_main_bf(const u16* __restrict__ Ap, int lda, const u16* __restrict__ Wt, f32x16 (&acc)[2][2], char* smem, float* rinv_s) {
;     ...
;   __builtin_amdgcn_s_setprio(0);
;   BLOAD(a0, b0, 0); BLOAD(a1, b1, 1);
;   __syncthreads();
;   BSTORE(a0, b0, 0);
;   BLOAD(a0, b0, 2);
;   __syncthreads();
; #pragma unroll
;   for (int kt = 0; kt < nk; kt += 2) {
;     BCOMP(0);
;     BSTORE(a1, b1, 1);
;     if (kt + 3 < nk) BLOAD(a1, b1, kt + 3);
;     __syncthreads();
;     BCOMP(1);
;     if (kt + 2 < nk) { BSTORE(a0, b0, 0); if (kt + 4 < nk) BLOAD(a0, b0, kt + 4); }
;     __syncthreads();
;   }
; DI void tile_branch(const Params& p, int l, int tile, char* smem) {
;     ...
;     f32x16 acc[2][2]; zero_acc(acc);
;     gemm_main_bf<false, 8>((const u16*)(p.ws + OFF_BR) + (size_t)(br * CT + m0) * 512, 512,
;                             (const u16*)(p.ws + OFF_WBR + (l * 3 + br) * SZ_WBR) + (size_t)n0 * 512, acc, smem, nullptr);
	ds_read_b128 v[208:211], v240 offset:16384
	ds_read_b128 v[224:227], v241 offset:16384
	ds_read_b128 v[228:231], v241 offset:17408
	ds_read_b128 v[232:235], v241 offset:18432
	ds_read_b128 v[236:239], v241 offset:19456
	s_add_u32 m0, s52, 0x0
	s_add_u32 s28, s28, 0x40
	s_addc_u32 s29, s29, 0
	global_load_lds_dwordx4 v244, s[28:29]
	global_load_lds_dwordx4 v245, s[28:29] offset:1024
	s_add_u32 m0, s53, 0x0
	s_add_u32 s30, s30, 0x10000
	s_addc_u32 s31, s31, 0
	global_load_lds_dwordx4 v251, s[30:31]
	global_load_lds_dwordx4 v251, s[30:31] offset:1024
	ds_read_b128 v[212:215], v240 offset:17408
	ds_read_b128 v[216:219], v240 offset:18432
	ds_read_b128 v[220:223], v240 offset:19456
	s_waitcnt lgkmcnt(6)
	v_mfma_f32_16x16x32_bf16 v[2:5], v[224:227], v[208:211], v[2:5]
	s_waitcnt lgkmcnt(5)
	v_mfma_f32_16x16x32_bf16 v[6:9], v[228:231], v[208:211], v[6:9]
	s_waitcnt lgkmcnt(4)
	v_mfma_f32_16x16x32_bf16 v[10:13], v[232:235], v[208:211], v[10:13]
	s_waitcnt lgkmcnt(3)
	v_mfma_f32_16x16x32_bf16 v[14:17], v[236:239], v[208:211], v[14:17]
	s_waitcnt lgkmcnt(2)
	v_mfma_f32_16x16x32_bf16 v[18:21], v[224:227], v[212:215], v[18:21]
	v_mfma_f32_16x16x32_bf16 v[22:25], v[228:231], v[212:215], v[22:25]
	v_mfma_f32_16x16x32_bf16 v[26:29], v[232:235], v[212:215], v[26:29]
	v_mfma_f32_16x16x32_bf16 v[30:33], v[236:239], v[212:215], v[30:33]
	s_waitcnt lgkmcnt(1)
	v_mfma_f32_16x16x32_bf16 v[34:37], v[224:227], v[216:219], v[34:37]
	v_mfma_f32_16x16x32_bf16 v[38:41], v[228:231], v[216:219], v[38:41]
	v_mfma_f32_16x16x32_bf16 v[42:45], v[232:235], v[216:219], v[42:45]
	v_mfma_f32_16x16x32_bf16 v[46:49], v[236:239], v[216:219], v[46:49]
	s_waitcnt lgkmcnt(0)
	v_mfma_f32_16x16x32_bf16 v[50:53], v[224:227], v[220:223], v[50:53]
	v_mfma_f32_16x16x32_bf16 v[54:57], v[228:231], v[220:223], v[54:57]
	v_mfma_f32_16x16x32_bf16 v[58:61], v[232:235], v[220:223], v[58:61]
	v_mfma_f32_16x16x32_bf16 v[62:65], v[236:239], v[220:223], v[62:65]
	s_waitcnt vmcnt(8)
	s_barrier
	ds_read_b128 v[208:211], v240 offset:32768
	ds_read_b128 v[224:227], v241 offset:32768
	ds_read_b128 v[228:231], v241 offset:33792
	ds_read_b128 v[232:235], v241 offset:34816
	ds_read_b128 v[236:239], v241 offset:35840
	s_add_u32 m0, s52, 0x4000
	s_add_u32 s28, s28, 0x40
	s_addc_u32 s29, s29, 0
	global_load_lds_dwordx4 v244, s[28:29]
	global_load_lds_dwordx4 v245, s[28:29] offset:1024
	s_add_u32 m0, s53, 0x4000
	s_add_u32 s30, s30, 0x10000
	s_addc_u32 s31, s31, 0
	global_load_lds_dwordx4 v251, s[30:31]
	global_load_lds_dwordx4 v251, s[30:31] offset:1024
	ds_read_b128 v[212:215], v240 offset:33792
	ds_read_b128 v[216:219], v240 offset:34816
	ds_read_b128 v[220:223], v240 offset:35840
	s_waitcnt lgkmcnt(6)
	v_mfma_f32_16x16x32_bf16 v[2:5], v[224:227], v[208:211], v[2:5]
	s_waitcnt lgkmcnt(5)
	v_mfma_f32_16x16x32_bf16 v[6:9], v[228:231], v[208:211], v[6:9]
	s_waitcnt lgkmcnt(4)
	v_mfma_f32_16x16x32_bf16 v[10:13], v[232:235], v[208:211], v[10:13]
	s_waitcnt lgkmcnt(3)
	v_mfma_f32_16x16x32_bf16 v[14:17], v[236:239], v[208:211], v[14:17]
	s_waitcnt lgkmcnt(2)
	v_mfma_f32_16x16x32_bf16 v[18:21], v[224:227], v[212:215], v[18:21]
	v_mfma_f32_16x16x32_bf16 v[22:25], v[228:231], v[212:215], v[22:25]
	v_mfma_f32_16x16x32_bf16 v[26:29], v[232:235], v[212:215], v[26:29]
	v_mfma_f32_16x16x32_bf16 v[30:33], v[236:239], v[212:215], v[30:33]
	s_waitcnt lgkmcnt(1)
	v_mfma_f32_16x16x32_bf16 v[34:37], v[224:227], v[216:219], v[34:37]
	v_mfma_f32_16x16x32_bf16 v[38:41], v[228:231], v[216:219], v[38:41]
	v_mfma_f32_16x16x32_bf16 v[42:45], v[232:235], v[216:219], v[42:45]
	v_mfma_f32_16x16x32_bf16 v[46:49], v[236:239], v[216:219], v[46:49]
	s_waitcnt lgkmcnt(0)
	v_mfma_f32_16x16x32_bf16 v[50:53], v[224:227], v[220:223], v[50:53]
	v_mfma_f32_16x16x32_bf16 v[54:57], v[228:231], v[220:223], v[54:57]
	v_mfma_f32_16x16x32_bf16 v[58:61], v[232:235], v[220:223], v[58:61]
	v_mfma_f32_16x16x32_bf16 v[62:65], v[236:239], v[220:223], v[62:65]
	s_waitcnt vmcnt(8)
	s_barrier
	ds_read_b128 v[208:211], v240 offset:49152
	ds_read_b128 v[224:227], v241 offset:49152
	ds_read_b128 v[228:231], v241 offset:50176
	ds_read_b128 v[232:235], v241 offset:51200
	ds_read_b128 v[236:239], v241 offset:52224
	s_add_u32 m0, s52, 0x8000
	s_add_u32 s28, s28, 0x40
	s_addc_u32 s29, s29, 0
	global_load_lds_dwordx4 v244, s[28:29]
	global_load_lds_dwordx4 v245, s[28:29] offset:1024
	s_add_u32 m0, s53, 0x8000
	s_add_u32 s30, s30, 0x10000
	s_addc_u32 s31, s31, 0
	global_load_lds_dwordx4 v251, s[30:31]
	global_load_lds_dwordx4 v251, s[30:31] offset:1024
	ds_read_b128 v[212:215], v240 offset:50176
	ds_read_b128 v[216:219], v240 offset:51200
	ds_read_b128 v[220:223], v240 offset:52224
	s_waitcnt lgkmcnt(6)
	v_mfma_f32_16x16x32_bf16 v[2:5], v[224:227], v[208:211], v[2:5]
	s_waitcnt lgkmcnt(5)
	v_mfma_f32_16x16x32_bf16 v[6:9], v[228:231], v[208:211], v[6:9]
	s_waitcnt lgkmcnt(4)
	v_mfma_f32_16x16x32_bf16 v[10:13], v[232:235], v[208:211], v[10:13]
	s_waitcnt lgkmcnt(3)
	v_mfma_f32_16x16x32_bf16 v[14:17], v[236:239], v[208:211], v[14:17]
	s_waitcnt lgkmcnt(2)
	v_mfma_f32_16x16x32_bf16 v[18:21], v[224:227], v[212:215], v[18:21]
	v_mfma_f32_16x16x32_bf16 v[22:25], v[228:231], v[212:215], v[22:25]
	v_mfma_f32_16x16x32_bf16 v[26:29], v[232:235], v[212:215], v[26:29]
	v_mfma_f32_16x16x32_bf16 v[30:33], v[236:239], v[212:215], v[30:33]
	s_waitcnt lgkmcnt(1)
	v_mfma_f32_16x16x32_bf16 v[34:37], v[224:227], v[216:219], v[34:37]
	v_mfma_f32_16x16x32_bf16 v[38:41], v[228:231], v[216:219], v[38:41]
	v_mfma_f32_16x16x32_bf16 v[42:45], v[232:235], v[216:219], v[42:45]
	v_mfma_f32_16x16x32_bf16 v[46:49], v[236:239], v[216:219], v[46:49]
	s_waitcnt lgkmcnt(0)
	v_mfma_f32_16x16x32_bf16 v[50:53], v[224:227], v[220:223], v[50:53]
	v_mfma_f32_16x16x32_bf16 v[54:57], v[228:231], v[220:223], v[54:57]
	v_mfma_f32_16x16x32_bf16 v[58:61], v[232:235], v[220:223], v[58:61]
	v_mfma_f32_16x16x32_bf16 v[62:65], v[236:239], v[220:223], v[62:65]
	s_mov_b32 s74, 2
	.p2align 6

; #define BLOAD(A_, B_, kt) do { _Pragma("unroll") for (int i = 0; i < 4; ++i) { \
;     A_[i] = *(const u32x4*)((const char*)Ap + (aoff + (unsigned)(32 * i * lda + (kt) * 64) * 2u)); B_[i] = *(const u32x4*)((const char*)Wt + (woff + (unsigned)(32 * i * K + (kt) * 64) * 2u)); } } while (0)
; #define BLOAD(A_, B_, kt) do { _Pragma("unroll") for (int i = 0; i < 4; ++i) { \
;     A_[i] = *(const u32x4*)((const char*)Ap + (aoff + (unsigned)(32 * i * lda + (kt) * 64) * 2u)); B_[i] = *(const u32x4*)((const char*)Wt + (woff + (unsigned)(32 * i * K + (kt) * 64) * 2u)); } } while (0)
; #define BSTORE(A_, B_, buf) do { _Pragma("unroll") for (int i = 0; i < 4; ++i) { \
;     *(u32x4*)&As[(buf) * GBUF + (srow + 32 * i) * LDT + sc8] = A_[i]; \
;     *(u32x4*)&Bs[(buf) * GBUF + (srow + 32 * i) * LDT + sc8] = B_[i]; } } while (0)
; template <int NK>
; DI void gemm_run(PF& pf, const u16* __restrict__ Ap, int lda, const u16* __restrict__ Wt, f32x16 (&acc)[2][2], char* smem) {
;     ...
;   __builtin_amdgcn_s_setprio(0);
;   __syncthreads();
;   BSTORE(pf.a0, pf.b0, 0);
;   BLOAD(pf.a0, pf.b0, 2);
;   __syncthreads();
; #pragma unroll
;   for (int kt = 0; kt < nk; kt += 2) {
;     BCOMP(0);
;     BSTORE(pf.a1, pf.b1, 1);
;     if (kt + 3 < nk) BLOAD(pf.a1, pf.b1, kt + 3);
;     __syncthreads();
;     BCOMP(1);
;     if (kt + 2 < nk) { BSTORE(pf.a0, pf.b0, 0); if (kt + 4 < nk) BLOAD(pf.a0, pf.b0, kt + 4); }
;     __syncthreads();
;   }
; DI void tile_inproj(const Params& p, int l, const Chunk& ck, int tile, int next, PF& pf, char* smem) {
;     ...
;   } else if (ni < 36) {
;     const int g = (ni - 24) >> 2, h = (ni - 24) & 3; const int dsh = 2 * g, d = 1 << dsh, Lg = S >> dsh;
;     const int col = tid & 127, c0 = tid >> 7; const int blk = m0 >> ck.sshift, t0 = m0 & (S - 1), ub = t0 >> dsh;
;     u16* dstb = (u16*)(p.ws + OFF_VDT) + ((size_t)((g * ck.nb + blk) * 4 + h) * 128 + col) * S;
.Linp_nokr:
	s_barrier
	s_mov_b32 s15, 0
	s_cmp_lt_u32 s30, 24
	s_cbranch_scc1 .Linp_dirk
	s_cmp_gt_u32 s30, 35
	s_cbranch_scc1 .Linp_dirk
	s_add_u32 m0, s46, 0x0
	s_nop 0
	global_load_lds_dwordx4 v138, s[48:49]
	global_load_lds_dwordx4 v139, s[48:49] offset:1024
	s_add_u32 m0, s47, 0x0
	s_nop 0
	global_load_lds_dwordx4 v140, s[50:51]
	global_load_lds_dwordx4 v141, s[50:51] offset:1024
	global_load_lds_dwordx4 v142, s[50:51] offset:2048
	global_load_lds_dwordx4 v143, s[50:51] offset:3072
	s_add_u32 m0, s46, 0x6000
	s_add_u32 s48, s48, 0x100000
	s_addc_u32 s49, s49, 0
	global_load_lds_dwordx4 v138, s[48:49]
	global_load_lds_dwordx4 v139, s[48:49] offset:1024
	s_add_u32 m0, s47, 0x6000
	s_add_u32 s50, s50, s13
	s_addc_u32 s51, s51, 0
	global_load_lds_dwordx4 v140, s[50:51]
	global_load_lds_dwordx4 v141, s[50:51] offset:1024
	global_load_lds_dwordx4 v142, s[50:51] offset:2048
	global_load_lds_dwordx4 v143, s[50:51] offset:3072
	s_waitcnt vmcnt(6)
	s_barrier
	ds_read_b128 v[224:227], v126 offset:0
	ds_read_b128 v[240:243], v128 offset:0
	ds_read_b128 v[244:247], v128 offset:1024
	ds_read_b128 v[248:251], v128 offset:2048
	ds_read_b128 v[156:159], v128 offset:3072
	s_add_u32 m0, s46, 0xc000
	s_add_u32 s48, s48, 0x100000
	s_addc_u32 s49, s49, 0
	global_load_lds_dwordx4 v138, s[48:49]
	global_load_lds_dwordx4 v139, s[48:49] offset:1024
	s_add_u32 m0, s47, 0xc000
	s_add_u32 s50, s50, s13
	s_addc_u32 s51, s51, 0
	global_load_lds_dwordx4 v140, s[50:51]
	global_load_lds_dwordx4 v141, s[50:51] offset:1024
	global_load_lds_dwordx4 v142, s[50:51] offset:2048
	global_load_lds_dwordx4 v143, s[50:51] offset:3072
	ds_read_b128 v[228:231], v126 offset:1024
	ds_read_b128 v[232:235], v126 offset:2048
	ds_read_b128 v[236:239], v126 offset:3072
	ds_read_b128 v[160:163], v128 offset:8192
	ds_read_b128 v[164:167], v128 offset:9216
	ds_read_b128 v[168:171], v128 offset:10240
	ds_read_b128 v[122:125], v128 offset:11264
	s_waitcnt lgkmcnt(10)
	v_mfma_f32_16x16x32_bf16 v[2:5], v[224:227], v[240:243], 0
	s_waitcnt lgkmcnt(9)
	v_mfma_f32_16x16x32_bf16 v[6:9], v[224:227], v[244:247], 0
	s_waitcnt lgkmcnt(8)
	v_mfma_f32_16x16x32_bf16 v[10:13], v[224:227], v[248:251], 0
	s_waitcnt lgkmcnt(7)
	v_mfma_f32_16x16x32_bf16 v[14:17], v[224:227], v[156:159], 0
	s_waitcnt lgkmcnt(6)
	v_mfma_f32_16x16x32_bf16 v[18:21], v[228:231], v[240:243], 0
	v_mfma_f32_16x16x32_bf16 v[22:25], v[228:231], v[244:247], 0
	v_mfma_f32_16x16x32_bf16 v[26:29], v[228:231], v[248:251], 0
	v_mfma_f32_16x16x32_bf16 v[30:33], v[228:231], v[156:159], 0
	s_waitcnt lgkmcnt(5)
	v_mfma_f32_16x16x32_bf16 v[34:37], v[232:235], v[240:243], 0
	v_mfma_f32_16x16x32_bf16 v[38:41], v[232:235], v[244:247], 0
	v_mfma_f32_16x16x32_bf16 v[42:45], v[232:235], v[248:251], 0
	v_mfma_f32_16x16x32_bf16 v[46:49], v[232:235], v[156:159], 0
	s_waitcnt lgkmcnt(4)
	v_mfma_f32_16x16x32_bf16 v[50:53], v[236:239], v[240:243], 0
	v_mfma_f32_16x16x32_bf16 v[54:57], v[236:239], v[244:247], 0
	v_mfma_f32_16x16x32_bf16 v[58:61], v[236:239], v[248:251], 0
	v_mfma_f32_16x16x32_bf16 v[62:65], v[236:239], v[156:159], 0
	s_waitcnt lgkmcnt(3)
	v_mfma_f32_16x16x32_bf16 v[74:77], v[224:227], v[160:163], 0
	s_waitcnt lgkmcnt(2)
	v_mfma_f32_16x16x32_bf16 v[78:81], v[224:227], v[164:167], 0
	s_waitcnt lgkmcnt(1)
	v_mfma_f32_16x16x32_bf16 v[82:85], v[224:227], v[168:171], 0
	s_waitcnt lgkmcnt(0)
	v_mfma_f32_16x16x32_bf16 v[86:89], v[224:227], v[122:125], 0
	v_mfma_f32_16x16x32_bf16 v[90:93], v[228:231], v[160:163], 0
	v_mfma_f32_16x16x32_bf16 v[94:97], v[228:231], v[164:167], 0
	v_mfma_f32_16x16x32_bf16 v[98:101], v[228:231], v[168:171], 0
	v_mfma_f32_16x16x32_bf16 v[102:105], v[228:231], v[122:125], 0
	v_mfma_f32_16x16x32_bf16 v[106:109], v[232:235], v[160:163], 0
	v_mfma_f32_16x16x32_bf16 v[110:113], v[232:235], v[164:167], 0
	v_mfma_f32_16x16x32_bf16 v[114:117], v[232:235], v[168:171], 0
	v_mfma_f32_16x16x32_bf16 v[118:121], v[232:235], v[122:125], 0
	v_mfma_f32_16x16x32_bf16 v[208:211], v[236:239], v[160:163], 0
	v_mfma_f32_16x16x32_bf16 v[212:215], v[236:239], v[164:167], 0
	v_mfma_f32_16x16x32_bf16 v[216:219], v[236:239], v[168:171], 0
	v_mfma_f32_16x16x32_bf16 v[220:223], v[236:239], v[122:125], 0
	s_waitcnt vmcnt(6)
	s_barrier
; #define BLOAD(A_, B_, kt) do { _Pragma("unroll") for (int i = 0; i < 4; ++i) { \
;     A_[i] = *(const u32x4*)((const char*)Ap + (aoff + (unsigned)(32 * i * lda + (kt) * 64) * 2u)); B_[i] = *(const u32x4*)((const char*)Wt + (woff + (unsigned)(32 * i * K + (kt) * 64) * 2u)); } } while (0)
; #define BLOAD(A_, B_, kt) do { _Pragma("unroll") for (int i = 0; i < 4; ++i) { \
;     A_[i] = *(const u32x4*)((const char*)Ap + (aoff + (unsigned)(32 * i * lda + (kt) * 64) * 2u)); B_[i] = *(const u32x4*)((const char*)Wt + (woff + (unsigned)(32 * i * K + (kt) * 64) * 2u)); } } while (0)
; #define BSTORE(A_, B_, buf) do { _Pragma("unroll") for (int i = 0; i < 4; ++i) { \
;     *(u32x4*)&As[(buf) * GBUF + (srow + 32 * i) * LDT + sc8] = A_[i]; \
;     *(u32x4*)&Bs[(buf) * GBUF + (srow + 32 * i) * LDT + sc8] = B_[i]; } } while (0)
; template <int NK>
; DI void gemm_run(PF& pf, const u16* __restrict__ Ap, int lda, const u16* __restrict__ Wt, f32x16 (&acc)[2][2], char* smem) {
;     ...
;   __builtin_amdgcn_s_setprio(0);
;   __syncthreads();
;   BSTORE(pf.a0, pf.b0, 0);
;   BLOAD(pf.a0, pf.b0, 2);
;   __syncthreads();
; #pragma unroll
;   for (int kt = 0; kt < nk; kt += 2) {
;     BCOMP(0);
;     BSTORE(pf.a1, pf.b1, 1);
;     if (kt + 3 < nk) BLOAD(pf.a1, pf.b1, kt + 3);
;     __syncthreads();
;     BCOMP(1);
;     if (kt + 2 < nk) { BSTORE(pf.a0, pf.b0, 0); if (kt + 4 < nk) BLOAD(pf.a0, pf.b0, kt + 4); }
;     __syncthreads();
;   }
	ds_read_b128 v[224:227], v126 offset:24576
	ds_read_b128 v[240:243], v128 offset:24576
	ds_read_b128 v[244:247], v128 offset:25600
	ds_read_b128 v[248:251], v128 offset:26624
	ds_read_b128 v[156:159], v128 offset:27648
	s_add_u32 m0, s46, 0x0
	s_add_u32 s48, s48, 0x100000
	s_addc_u32 s49, s49, 0
	global_load_lds_dwordx4 v138, s[48:49]
	global_load_lds_dwordx4 v139, s[48:49] offset:1024
	s_add_u32 m0, s47, 0x0
	s_add_u32 s50, s50, s13
	s_addc_u32 s51, s51, 0
	global_load_lds_dwordx4 v140, s[50:51]
	global_load_lds_dwordx4 v141, s[50:51] offset:1024
	global_load_lds_dwordx4 v142, s[50:51] offset:2048
	global_load_lds_dwordx4 v143, s[50:51] offset:3072
	ds_read_b128 v[228:231], v126 offset:25600
	ds_read_b128 v[232:235], v126 offset:26624
	ds_read_b128 v[236:239], v126 offset:27648
	ds_read_b128 v[160:163], v128 offset:32768
	ds_read_b128 v[164:167], v128 offset:33792
	ds_read_b128 v[168:171], v128 offset:34816
	ds_read_b128 v[122:125], v128 offset:35840
	s_waitcnt lgkmcnt(10)
	v_mfma_f32_16x16x32_bf16 v[2:5], v[224:227], v[240:243], v[2:5]
	s_waitcnt lgkmcnt(9)
	v_mfma_f32_16x16x32_bf16 v[6:9], v[224:227], v[244:247], v[6:9]
	s_waitcnt lgkmcnt(8)
	v_mfma_f32_16x16x32_bf16 v[10:13], v[224:227], v[248:251], v[10:13]
	s_waitcnt lgkmcnt(7)
	v_mfma_f32_16x16x32_bf16 v[14:17], v[224:227], v[156:159], v[14:17]
	s_waitcnt lgkmcnt(6)
	v_mfma_f32_16x16x32_bf16 v[18:21], v[228:231], v[240:243], v[18:21]
	v_mfma_f32_16x16x32_bf16 v[22:25], v[228:231], v[244:247], v[22:25]
	v_mfma_f32_16x16x32_bf16 v[26:29], v[228:231], v[248:251], v[26:29]
	v_mfma_f32_16x16x32_bf16 v[30:33], v[228:231], v[156:159], v[30:33]
	s_waitcnt lgkmcnt(5)
	v_mfma_f32_16x16x32_bf16 v[34:37], v[232:235], v[240:243], v[34:37]
	v_mfma_f32_16x16x32_bf16 v[38:41], v[232:235], v[244:247], v[38:41]
	v_mfma_f32_16x16x32_bf16 v[42:45], v[232:235], v[248:251], v[42:45]
	v_mfma_f32_16x16x32_bf16 v[46:49], v[232:235], v[156:159], v[46:49]
	s_waitcnt lgkmcnt(4)
	v_mfma_f32_16x16x32_bf16 v[50:53], v[236:239], v[240:243], v[50:53]
	v_mfma_f32_16x16x32_bf16 v[54:57], v[236:239], v[244:247], v[54:57]
	v_mfma_f32_16x16x32_bf16 v[58:61], v[236:239], v[248:251], v[58:61]
	v_mfma_f32_16x16x32_bf16 v[62:65], v[236:239], v[156:159], v[62:65]
	s_waitcnt lgkmcnt(3)
	v_mfma_f32_16x16x32_bf16 v[74:77], v[224:227], v[160:163], v[74:77]
	s_waitcnt lgkmcnt(2)
	v_mfma_f32_16x16x32_bf16 v[78:81], v[224:227], v[164:167], v[78:81]
	s_waitcnt lgkmcnt(1)
	v_mfma_f32_16x16x32_bf16 v[82:85], v[224:227], v[168:171], v[82:85]
	s_waitcnt lgkmcnt(0)
	v_mfma_f32_16x16x32_bf16 v[86:89], v[224:227], v[122:125], v[86:89]
	v_mfma_f32_16x16x32_bf16 v[90:93], v[228:231], v[160:163], v[90:93]
	v_mfma_f32_16x16x32_bf16 v[94:97], v[228:231], v[164:167], v[94:97]
	v_mfma_f32_16x16x32_bf16 v[98:101], v[228:231], v[168:171], v[98:101]
	v_mfma_f32_16x16x32_bf16 v[102:105], v[228:231], v[122:125], v[102:105]
	v_mfma_f32_16x16x32_bf16 v[106:109], v[232:235], v[160:163], v[106:109]
	v_mfma_f32_16x16x32_bf16 v[110:113], v[232:235], v[164:167], v[110:113]
	v_mfma_f32_16x16x32_bf16 v[114:117], v[232:235], v[168:171], v[114:117]
	v_mfma_f32_16x16x32_bf16 v[118:121], v[232:235], v[122:125], v[118:121]
	v_mfma_f32_16x16x32_bf16 v[208:211], v[236:239], v[160:163], v[208:211]
	v_mfma_f32_16x16x32_bf16 v[212:215], v[236:239], v[164:167], v[212:215]
	v_mfma_f32_16x16x32_bf16 v[216:219], v[236:239], v[168:171], v[216:219]
	v_mfma_f32_16x16x32_bf16 v[220:223], v[236:239], v[122:125], v[220:223]
	s_waitcnt vmcnt(6)
	s_barrier
	ds_read_b128 v[224:227], v126 offset:49152
	ds_read_b128 v[240:243], v128 offset:49152
	ds_read_b128 v[244:247], v128 offset:50176
	ds_read_b128 v[248:251], v128 offset:51200
	ds_read_b128 v[156:159], v128 offset:52224
	s_add_u32 m0, s46, 0x6000
	s_add_u32 s48, s48, 0x100000
	s_addc_u32 s49, s49, 0
	global_load_lds_dwordx4 v138, s[48:49]
	global_load_lds_dwordx4 v139, s[48:49] offset:1024
	s_add_u32 m0, s47, 0x6000
	s_add_u32 s50, s50, s13
	s_addc_u32 s51, s51, 0
	global_load_lds_dwordx4 v140, s[50:51]
	global_load_lds_dwordx4 v141, s[50:51] offset:1024
	global_load_lds_dwordx4 v142, s[50:51] offset:2048
	global_load_lds_dwordx4 v143, s[50:51] offset:3072
	ds_read_b128 v[228:231], v126 offset:50176
	ds_read_b128 v[232:235], v126 offset:51200
	ds_read_b128 v[236:239], v126 offset:52224
	ds_read_b128 v[160:163], v128 offset:57344
	ds_read_b128 v[164:167], v128 offset:58368
	ds_read_b128 v[168:171], v128 offset:59392
	ds_read_b128 v[122:125], v128 offset:60416
	s_waitcnt lgkmcnt(10)
	v_mfma_f32_16x16x32_bf16 v[2:5], v[224:227], v[240:243], v[2:5]
	s_waitcnt lgkmcnt(9)
	v_mfma_f32_16x16x32_bf16 v[6:9], v[224:227], v[244:247], v[6:9]
	s_waitcnt lgkmcnt(8)
	v_mfma_f32_16x16x32_bf16 v[10:13], v[224:227], v[248:251], v[10:13]
	s_waitcnt lgkmcnt(7)
	v_mfma_f32_16x16x32_bf16 v[14:17], v[224:227], v[156:159], v[14:17]
	s_waitcnt lgkmcnt(6)
	v_mfma_f32_16x16x32_bf16 v[18:21], v[228:231], v[240:243], v[18:21]
	v_mfma_f32_16x16x32_bf16 v[22:25], v[228:231], v[244:247], v[22:25]
	v_mfma_f32_16x16x32_bf16 v[26:29], v[228:231], v[248:251], v[26:29]
	v_mfma_f32_16x16x32_bf16 v[30:33], v[228:231], v[156:159], v[30:33]
	s_waitcnt lgkmcnt(5)
	v_mfma_f32_16x16x32_bf16 v[34:37], v[232:235], v[240:243], v[34:37]
	v_mfma_f32_16x16x32_bf16 v[38:41], v[232:235], v[244:247], v[38:41]
	v_mfma_f32_16x16x32_bf16 v[42:45], v[232:235], v[248:251], v[42:45]
	v_mfma_f32_16x16x32_bf16 v[46:49], v[232:235], v[156:159], v[46:49]
	s_waitcnt lgkmcnt(4)
	v_mfma_f32_16x16x32_bf16 v[50:53], v[236:239], v[240:243], v[50:53]
	v_mfma_f32_16x16x32_bf16 v[54:57], v[236:239], v[244:247], v[54:57]
	v_mfma_f32_16x16x32_bf16 v[58:61], v[236:239], v[248:251], v[58:61]
	v_mfma_f32_16x16x32_bf16 v[62:65], v[236:239], v[156:159], v[62:65]
	s_waitcnt lgkmcnt(3)
	v_mfma_f32_16x16x32_bf16 v[74:77], v[224:227], v[160:163], v[74:77]
	s_waitcnt lgkmcnt(2)
	v_mfma_f32_16x16x32_bf16 v[78:81], v[224:227], v[164:167], v[78:81]
	s_waitcnt lgkmcnt(1)
	v_mfma_f32_16x16x32_bf16 v[82:85], v[224:227], v[168:171], v[82:85]
	s_waitcnt lgkmcnt(0)
	v_mfma_f32_16x16x32_bf16 v[86:89], v[224:227], v[122:125], v[86:89]
	v_mfma_f32_16x16x32_bf16 v[90:93], v[228:231], v[160:163], v[90:93]
	v_mfma_f32_16x16x32_bf16 v[94:97], v[228:231], v[164:167], v[94:97]
	v_mfma_f32_16x16x32_bf16 v[98:101], v[228:231], v[168:171], v[98:101]
	v_mfma_f32_16x16x32_bf16 v[102:105], v[228:231], v[122:125], v[102:105]
	v_mfma_f32_16x16x32_bf16 v[106:109], v[232:235], v[160:163], v[106:109]
	v_mfma_f32_16x16x32_bf16 v[110:113], v[232:235], v[164:167], v[110:113]
	v_mfma_f32_16x16x32_bf16 v[114:117], v[232:235], v[168:171], v[114:117]
	v_mfma_f32_16x16x32_bf16 v[118:121], v[232:235], v[122:125], v[118:121]
	v_mfma_f32_16x16x32_bf16 v[208:211], v[236:239], v[160:163], v[208:211]
	v_mfma_f32_16x16x32_bf16 v[212:215], v[236:239], v[164:167], v[212:215]
	v_mfma_f32_16x16x32_bf16 v[216:219], v[236:239], v[168:171], v[216:219]
	v_mfma_f32_16x16x32_bf16 v[220:223], v[236:239], v[122:125], v[220:223]
	s_mov_b32 s12, 9
	.p2align 6

; #define BLOAD(A_, B_, kt) do { _Pragma("unroll") for (int i = 0; i < 4; ++i) { \
;     A_[i] = *(const u32x4*)((const char*)Ap + (aoff + (unsigned)(32 * i * lda + (kt) * 64) * 2u)); B_[i] = *(const u32x4*)((const char*)Wt + (woff + (unsigned)(32 * i * K + (kt) * 64) * 2u)); } } while (0)
; #define BLOAD(A_, B_, kt) do { _Pragma("unroll") for (int i = 0; i < 4; ++i) { \
;     A_[i] = *(const u32x4*)((const char*)Ap + (aoff + (unsigned)(32 * i * lda + (kt) * 64) * 2u)); B_[i] = *(const u32x4*)((const char*)Wt + (woff + (unsigned)(32 * i * K + (kt) * 64) * 2u)); } } while (0)
; #define BSTORE(A_, B_, buf) do { _Pragma("unroll") for (int i = 0; i < 4; ++i) { \
;     *(u32x4*)&As[(buf) * GBUF + (srow + 32 * i) * LDT + sc8] = A_[i]; \
;     *(u32x4*)&Bs[(buf) * GBUF + (srow + 32 * i) * LDT + sc8] = B_[i]; } } while (0)
; template <int NK>
; DI void gemm_run(PF& pf, const u16* __restrict__ Ap, int lda, const u16* __restrict__ Wt, f32x16 (&acc)[2][2], char* smem) {
;     ...
;   __builtin_amdgcn_s_setprio(0);
;   __syncthreads();
;   BSTORE(pf.a0, pf.b0, 0);
;   BLOAD(pf.a0, pf.b0, 2);
;   __syncthreads();
; #pragma unroll
;   for (int kt = 0; kt < nk; kt += 2) {
;     BCOMP(0);
;     BSTORE(pf.a1, pf.b1, 1);
;     if (kt + 3 < nk) BLOAD(pf.a1, pf.b1, kt + 3);
;     __syncthreads();
;     BCOMP(1);
;     if (kt + 2 < nk) { BSTORE(pf.a0, pf.b0, 0); if (kt + 4 < nk) BLOAD(pf.a0, pf.b0, kt + 4); }
;     __syncthreads();
;   }
.Linp_dirk:
	s_mov_b32 s15, 1
	s_add_u32 m0, s46, 0x0
	s_nop 0
	global_load_lds_dwordx4 v138, s[48:49]
	global_load_lds_dwordx4 v139, s[48:49] offset:1024
	s_add_u32 m0, s47, 0x0
	s_nop 0
	global_load_lds_dwordx4 v140, s[50:51]
	global_load_lds_dwordx4 v141, s[50:51] offset:1024
	global_load_lds_dwordx4 v142, s[50:51] offset:2048
	global_load_lds_dwordx4 v143, s[50:51] offset:3072
	s_add_u32 m0, s46, 0x6000
	s_add_u32 s48, s48, 0x100000
	s_addc_u32 s49, s49, 0
	global_load_lds_dwordx4 v138, s[48:49]
	global_load_lds_dwordx4 v139, s[48:49] offset:1024
	s_add_u32 m0, s47, 0x6000
	s_add_u32 s50, s50, s13
	s_addc_u32 s51, s51, 0
	global_load_lds_dwordx4 v140, s[50:51]
	global_load_lds_dwordx4 v141, s[50:51] offset:1024
	global_load_lds_dwordx4 v142, s[50:51] offset:2048
	global_load_lds_dwordx4 v143, s[50:51] offset:3072
	s_waitcnt vmcnt(6)
	s_barrier
	ds_read_b128 v[224:227], v126 offset:0
	ds_read_b128 v[240:243], v128 offset:0
	ds_read_b128 v[244:247], v128 offset:1024
	ds_read_b128 v[248:251], v128 offset:2048
	ds_read_b128 v[156:159], v128 offset:3072
	s_add_u32 m0, s46, 0xc000
	s_add_u32 s48, s48, 0x100000
	s_addc_u32 s49, s49, 0
	global_load_lds_dwordx4 v138, s[48:49]
	global_load_lds_dwordx4 v139, s[48:49] offset:1024
	s_add_u32 m0, s47, 0xc000
	s_add_u32 s50, s50, s13
	s_addc_u32 s51, s51, 0
	global_load_lds_dwordx4 v140, s[50:51]
	global_load_lds_dwordx4 v141, s[50:51] offset:1024
	global_load_lds_dwordx4 v142, s[50:51] offset:2048
	global_load_lds_dwordx4 v143, s[50:51] offset:3072
	ds_read_b128 v[228:231], v126 offset:1024
	ds_read_b128 v[232:235], v126 offset:2048
	ds_read_b128 v[236:239], v126 offset:3072
	ds_read_b128 v[160:163], v128 offset:8192
	ds_read_b128 v[164:167], v128 offset:9216
	ds_read_b128 v[168:171], v128 offset:10240
	ds_read_b128 v[122:125], v128 offset:11264
	s_waitcnt lgkmcnt(10)
	v_mfma_f32_16x16x32_bf16 v[2:5], v[240:243], v[224:227], 0
	s_waitcnt lgkmcnt(9)
	v_mfma_f32_16x16x32_bf16 v[6:9], v[244:247], v[224:227], 0
	s_waitcnt lgkmcnt(8)
	v_mfma_f32_16x16x32_bf16 v[10:13], v[248:251], v[224:227], 0
	s_waitcnt lgkmcnt(7)
	v_mfma_f32_16x16x32_bf16 v[14:17], v[156:159], v[224:227], 0
	s_waitcnt lgkmcnt(6)
	v_mfma_f32_16x16x32_bf16 v[18:21], v[240:243], v[228:231], 0
	v_mfma_f32_16x16x32_bf16 v[22:25], v[244:247], v[228:231], 0
	v_mfma_f32_16x16x32_bf16 v[26:29], v[248:251], v[228:231], 0
	v_mfma_f32_16x16x32_bf16 v[30:33], v[156:159], v[228:231], 0
	s_waitcnt lgkmcnt(5)
	v_mfma_f32_16x16x32_bf16 v[34:37], v[240:243], v[232:235], 0
	v_mfma_f32_16x16x32_bf16 v[38:41], v[244:247], v[232:235], 0
	v_mfma_f32_16x16x32_bf16 v[42:45], v[248:251], v[232:235], 0
	v_mfma_f32_16x16x32_bf16 v[46:49], v[156:159], v[232:235], 0
	s_waitcnt lgkmcnt(4)
	v_mfma_f32_16x16x32_bf16 v[50:53], v[240:243], v[236:239], 0
	v_mfma_f32_16x16x32_bf16 v[54:57], v[244:247], v[236:239], 0
	v_mfma_f32_16x16x32_bf16 v[58:61], v[248:251], v[236:239], 0
	v_mfma_f32_16x16x32_bf16 v[62:65], v[156:159], v[236:239], 0
	s_waitcnt lgkmcnt(3)
	v_mfma_f32_16x16x32_bf16 v[74:77], v[160:163], v[224:227], 0
	s_waitcnt lgkmcnt(2)
	v_mfma_f32_16x16x32_bf16 v[78:81], v[164:167], v[224:227], 0
	s_waitcnt lgkmcnt(1)
	v_mfma_f32_16x16x32_bf16 v[82:85], v[168:171], v[224:227], 0
	s_waitcnt lgkmcnt(0)
	v_mfma_f32_16x16x32_bf16 v[86:89], v[122:125], v[224:227], 0
	v_mfma_f32_16x16x32_bf16 v[90:93], v[160:163], v[228:231], 0
	v_mfma_f32_16x16x32_bf16 v[94:97], v[164:167], v[228:231], 0
	v_mfma_f32_16x16x32_bf16 v[98:101], v[168:171], v[228:231], 0
	v_mfma_f32_16x16x32_bf16 v[102:105], v[122:125], v[228:231], 0
	v_mfma_f32_16x16x32_bf16 v[106:109], v[160:163], v[232:235], 0
	v_mfma_f32_16x16x32_bf16 v[110:113], v[164:167], v[232:235], 0
	v_mfma_f32_16x16x32_bf16 v[114:117], v[168:171], v[232:235], 0
	v_mfma_f32_16x16x32_bf16 v[118:121], v[122:125], v[232:235], 0
	v_mfma_f32_16x16x32_bf16 v[208:211], v[160:163], v[236:239], 0
	v_mfma_f32_16x16x32_bf16 v[212:215], v[164:167], v[236:239], 0
	v_mfma_f32_16x16x32_bf16 v[216:219], v[168:171], v[236:239], 0
	v_mfma_f32_16x16x32_bf16 v[220:223], v[122:125], v[236:239], 0
	s_waitcnt vmcnt(6)
	s_barrier
; #define BLOAD(A_, B_, kt) do { _Pragma("unroll") for (int i = 0; i < 4; ++i) { \
;     A_[i] = *(const u32x4*)((const char*)Ap + (aoff + (unsigned)(32 * i * lda + (kt) * 64) * 2u)); B_[i] = *(const u32x4*)((const char*)Wt + (woff + (unsigned)(32 * i * K + (kt) * 64) * 2u)); } } while (0)
; #define BLOAD(A_, B_, kt) do { _Pragma("unroll") for (int i = 0; i < 4; ++i) { \
;     A_[i] = *(const u32x4*)((const char*)Ap + (aoff + (unsigned)(32 * i * lda + (kt) * 64) * 2u)); B_[i] = *(const u32x4*)((const char*)Wt + (woff + (unsigned)(32 * i * K + (kt) * 64) * 2u)); } } while (0)
; #define BSTORE(A_, B_, buf) do { _Pragma("unroll") for (int i = 0; i < 4; ++i) { \
;     *(u32x4*)&As[(buf) * GBUF + (srow + 32 * i) * LDT + sc8] = A_[i]; \
;     *(u32x4*)&Bs[(buf) * GBUF + (srow + 32 * i) * LDT + sc8] = B_[i]; } } while (0)
; template <int NK>
; DI void gemm_run(PF& pf, const u16* __restrict__ Ap, int lda, const u16* __restrict__ Wt, f32x16 (&acc)[2][2], char* smem) {
;     ...
;   __builtin_amdgcn_s_setprio(0);
;   __syncthreads();
;   BSTORE(pf.a0, pf.b0, 0);
;   BLOAD(pf.a0, pf.b0, 2);
;   __syncthreads();
; #pragma unroll
;   for (int kt = 0; kt < nk; kt += 2) {
;     BCOMP(0);
;     BSTORE(pf.a1, pf.b1, 1);
;     if (kt + 3 < nk) BLOAD(pf.a1, pf.b1, kt + 3);
;     __syncthreads();
;     BCOMP(1);
;     if (kt + 2 < nk) { BSTORE(pf.a0, pf.b0, 0); if (kt + 4 < nk) BLOAD(pf.a0, pf.b0, kt + 4); }
;     __syncthreads();
;   }
	ds_read_b128 v[224:227], v126 offset:24576
	ds_read_b128 v[240:243], v128 offset:24576
	ds_read_b128 v[244:247], v128 offset:25600
	ds_read_b128 v[248:251], v128 offset:26624
	ds_read_b128 v[156:159], v128 offset:27648
	s_add_u32 m0, s46, 0x0
	s_add_u32 s48, s48, 0x100000
	s_addc_u32 s49, s49, 0
	global_load_lds_dwordx4 v138, s[48:49]
	global_load_lds_dwordx4 v139, s[48:49] offset:1024
	s_add_u32 m0, s47, 0x0
	s_add_u32 s50, s50, s13
	s_addc_u32 s51, s51, 0
	global_load_lds_dwordx4 v140, s[50:51]
	global_load_lds_dwordx4 v141, s[50:51] offset:1024
	global_load_lds_dwordx4 v142, s[50:51] offset:2048
	global_load_lds_dwordx4 v143, s[50:51] offset:3072
	ds_read_b128 v[228:231], v126 offset:25600
	ds_read_b128 v[232:235], v126 offset:26624
	ds_read_b128 v[236:239], v126 offset:27648
	ds_read_b128 v[160:163], v128 offset:32768
	ds_read_b128 v[164:167], v128 offset:33792
	ds_read_b128 v[168:171], v128 offset:34816
	ds_read_b128 v[122:125], v128 offset:35840
	s_waitcnt lgkmcnt(10)
	v_mfma_f32_16x16x32_bf16 v[2:5], v[240:243], v[224:227], v[2:5]
	s_waitcnt lgkmcnt(9)
	v_mfma_f32_16x16x32_bf16 v[6:9], v[244:247], v[224:227], v[6:9]
	s_waitcnt lgkmcnt(8)
	v_mfma_f32_16x16x32_bf16 v[10:13], v[248:251], v[224:227], v[10:13]
	s_waitcnt lgkmcnt(7)
	v_mfma_f32_16x16x32_bf16 v[14:17], v[156:159], v[224:227], v[14:17]
	s_waitcnt lgkmcnt(6)
	v_mfma_f32_16x16x32_bf16 v[18:21], v[240:243], v[228:231], v[18:21]
	v_mfma_f32_16x16x32_bf16 v[22:25], v[244:247], v[228:231], v[22:25]
	v_mfma_f32_16x16x32_bf16 v[26:29], v[248:251], v[228:231], v[26:29]
	v_mfma_f32_16x16x32_bf16 v[30:33], v[156:159], v[228:231], v[30:33]
	s_waitcnt lgkmcnt(5)
	v_mfma_f32_16x16x32_bf16 v[34:37], v[240:243], v[232:235], v[34:37]
	v_mfma_f32_16x16x32_bf16 v[38:41], v[244:247], v[232:235], v[38:41]
	v_mfma_f32_16x16x32_bf16 v[42:45], v[248:251], v[232:235], v[42:45]
	v_mfma_f32_16x16x32_bf16 v[46:49], v[156:159], v[232:235], v[46:49]
	s_waitcnt lgkmcnt(4)
	v_mfma_f32_16x16x32_bf16 v[50:53], v[240:243], v[236:239], v[50:53]
	v_mfma_f32_16x16x32_bf16 v[54:57], v[244:247], v[236:239], v[54:57]
	v_mfma_f32_16x16x32_bf16 v[58:61], v[248:251], v[236:239], v[58:61]
	v_mfma_f32_16x16x32_bf16 v[62:65], v[156:159], v[236:239], v[62:65]
	s_waitcnt lgkmcnt(3)
	v_mfma_f32_16x16x32_bf16 v[74:77], v[160:163], v[224:227], v[74:77]
	s_waitcnt lgkmcnt(2)
	v_mfma_f32_16x16x32_bf16 v[78:81], v[164:167], v[224:227], v[78:81]
	s_waitcnt lgkmcnt(1)
	v_mfma_f32_16x16x32_bf16 v[82:85], v[168:171], v[224:227], v[82:85]
	s_waitcnt lgkmcnt(0)
	v_mfma_f32_16x16x32_bf16 v[86:89], v[122:125], v[224:227], v[86:89]
	v_mfma_f32_16x16x32_bf16 v[90:93], v[160:163], v[228:231], v[90:93]
	v_mfma_f32_16x16x32_bf16 v[94:97], v[164:167], v[228:231], v[94:97]
	v_mfma_f32_16x16x32_bf16 v[98:101], v[168:171], v[228:231], v[98:101]
	v_mfma_f32_16x16x32_bf16 v[102:105], v[122:125], v[228:231], v[102:105]
	v_mfma_f32_16x16x32_bf16 v[106:109], v[160:163], v[232:235], v[106:109]
	v_mfma_f32_16x16x32_bf16 v[110:113], v[164:167], v[232:235], v[110:113]
	v_mfma_f32_16x16x32_bf16 v[114:117], v[168:171], v[232:235], v[114:117]
	v_mfma_f32_16x16x32_bf16 v[118:121], v[122:125], v[232:235], v[118:121]
	v_mfma_f32_16x16x32_bf16 v[208:211], v[160:163], v[236:239], v[208:211]
	v_mfma_f32_16x16x32_bf16 v[212:215], v[164:167], v[236:239], v[212:215]
	v_mfma_f32_16x16x32_bf16 v[216:219], v[168:171], v[236:239], v[216:219]
	v_mfma_f32_16x16x32_bf16 v[220:223], v[122:125], v[236:239], v[220:223]
	s_waitcnt vmcnt(6)
	s_barrier
	ds_read_b128 v[224:227], v126 offset:49152
	ds_read_b128 v[240:243], v128 offset:49152
	ds_read_b128 v[244:247], v128 offset:50176
	ds_read_b128 v[248:251], v128 offset:51200
	ds_read_b128 v[156:159], v128 offset:52224
	s_add_u32 m0, s46, 0x6000
	s_add_u32 s48, s48, 0x100000
	s_addc_u32 s49, s49, 0
	global_load_lds_dwordx4 v138, s[48:49]
	global_load_lds_dwordx4 v139, s[48:49] offset:1024
	s_add_u32 m0, s47, 0x6000
	s_add_u32 s50, s50, s13
	s_addc_u32 s51, s51, 0
	global_load_lds_dwordx4 v140, s[50:51]
	global_load_lds_dwordx4 v141, s[50:51] offset:1024
	global_load_lds_dwordx4 v142, s[50:51] offset:2048
	global_load_lds_dwordx4 v143, s[50:51] offset:3072
	ds_read_b128 v[228:231], v126 offset:50176
	ds_read_b128 v[232:235], v126 offset:51200
	ds_read_b128 v[236:239], v126 offset:52224
	ds_read_b128 v[160:163], v128 offset:57344
	ds_read_b128 v[164:167], v128 offset:58368
	ds_read_b128 v[168:171], v128 offset:59392
	ds_read_b128 v[122:125], v128 offset:60416
	s_waitcnt lgkmcnt(10)
	v_mfma_f32_16x16x32_bf16 v[2:5], v[240:243], v[224:227], v[2:5]
	s_waitcnt lgkmcnt(9)
	v_mfma_f32_16x16x32_bf16 v[6:9], v[244:247], v[224:227], v[6:9]
	s_waitcnt lgkmcnt(8)
	v_mfma_f32_16x16x32_bf16 v[10:13], v[248:251], v[224:227], v[10:13]
	s_waitcnt lgkmcnt(7)
	v_mfma_f32_16x16x32_bf16 v[14:17], v[156:159], v[224:227], v[14:17]
	s_waitcnt lgkmcnt(6)
	v_mfma_f32_16x16x32_bf16 v[18:21], v[240:243], v[228:231], v[18:21]
	v_mfma_f32_16x16x32_bf16 v[22:25], v[244:247], v[228:231], v[22:25]
	v_mfma_f32_16x16x32_bf16 v[26:29], v[248:251], v[228:231], v[26:29]
	v_mfma_f32_16x16x32_bf16 v[30:33], v[156:159], v[228:231], v[30:33]
	s_waitcnt lgkmcnt(5)
	v_mfma_f32_16x16x32_bf16 v[34:37], v[240:243], v[232:235], v[34:37]
	v_mfma_f32_16x16x32_bf16 v[38:41], v[244:247], v[232:235], v[38:41]
	v_mfma_f32_16x16x32_bf16 v[42:45], v[248:251], v[232:235], v[42:45]
	v_mfma_f32_16x16x32_bf16 v[46:49], v[156:159], v[232:235], v[46:49]
	s_waitcnt lgkmcnt(4)
	v_mfma_f32_16x16x32_bf16 v[50:53], v[240:243], v[236:239], v[50:53]
	v_mfma_f32_16x16x32_bf16 v[54:57], v[244:247], v[236:239], v[54:57]
	v_mfma_f32_16x16x32_bf16 v[58:61], v[248:251], v[236:239], v[58:61]
	v_mfma_f32_16x16x32_bf16 v[62:65], v[156:159], v[236:239], v[62:65]
	s_waitcnt lgkmcnt(3)
	v_mfma_f32_16x16x32_bf16 v[74:77], v[160:163], v[224:227], v[74:77]
	s_waitcnt lgkmcnt(2)
	v_mfma_f32_16x16x32_bf16 v[78:81], v[164:167], v[224:227], v[78:81]
	s_waitcnt lgkmcnt(1)
	v_mfma_f32_16x16x32_bf16 v[82:85], v[168:171], v[224:227], v[82:85]
	s_waitcnt lgkmcnt(0)
	v_mfma_f32_16x16x32_bf16 v[86:89], v[122:125], v[224:227], v[86:89]
	v_mfma_f32_16x16x32_bf16 v[90:93], v[160:163], v[228:231], v[90:93]
	v_mfma_f32_16x16x32_bf16 v[94:97], v[164:167], v[228:231], v[94:97]
	v_mfma_f32_16x16x32_bf16 v[98:101], v[168:171], v[228:231], v[98:101]
	v_mfma_f32_16x16x32_bf16 v[102:105], v[122:125], v[228:231], v[102:105]
	v_mfma_f32_16x16x32_bf16 v[106:109], v[160:163], v[232:235], v[106:109]
	v_mfma_f32_16x16x32_bf16 v[110:113], v[164:167], v[232:235], v[110:113]
	v_mfma_f32_16x16x32_bf16 v[114:117], v[168:171], v[232:235], v[114:117]
	v_mfma_f32_16x16x32_bf16 v[118:121], v[122:125], v[232:235], v[118:121]
	v_mfma_f32_16x16x32_bf16 v[208:211], v[160:163], v[236:239], v[208:211]
	v_mfma_f32_16x16x32_bf16 v[212:215], v[164:167], v[236:239], v[212:215]
	v_mfma_f32_16x16x32_bf16 v[216:219], v[168:171], v[236:239], v[216:219]
	v_mfma_f32_16x16x32_bf16 v[220:223], v[122:125], v[236:239], v[220:223]
	s_mov_b32 s12, 9
	.p2align 6
